# previous + residual-GEMM epilogue: batched x/gate loads with counted vmcnt instead of per-pair vmcnt(0)
# speedup vs baseline: 1.0018x; 1.0018x over previous
; template <int MI, int BM, int BN, class ACC>
; DI void resid_epi(const Prm& p, ACC& acc, int row0, int col0, int l, int gchunk, int lane) {
;     ...
;   for (int i = 0; i < MI; ++i) {
;     const int row = row0 + i * 16 + (lane & 15);
;     float* xr = xrow(p, row);
;     const float* xs = (l == 0 && gchunk == 2) ? xrow_in(p, row) : (const float*)xr;
;     const float* gt = mod + (size_t)(l * 2 + (row >= S ? 1 : 0)) * 6144 + gchunk * D;
; #pragma unroll
;     for (int j = 0; j < 4; ++j) {
;       const int col = col0 + j * 16 + 4 * (lane >> 4);
;       const float4 g4 = *(const float4*)(gt + col); float4 xv = *(const float4*)(xs + col);
;       xv.x += g4.x * acc[i][j][0]; xv.y += g4.y * acc[i][j][1]; xv.z += g4.z * acc[i][j][2]; xv.w += g4.w * acc[i][j][3];
;       *(float4*)(xr + col) = xv;
;     }
.LBB0_461:
	v_lshl_add_u32 v167, s30, 8, v238
	v_add_u32_e32 v162, 0xffffc000, v167
	v_cmp_gt_i32_e32 vcc, s73, v167
	v_readlane_b32 s0, v253, 58
	v_ashrrev_i32_e32 v163, 31, v167
	v_cndmask_b32_e32 v168, v162, v167, vcc
	v_mov_b32_e32 v162, s0
	v_readlane_b32 s0, v253, 57
	v_lshl_add_u32 v160, s31, 8, v239
	v_cndmask_b32_e32 v169, 0, v163, vcc
	v_mov_b32_e32 v163, s65
	v_mov_b32_e32 v164, s0
	v_mov_b32_e32 v165, s64
	v_readlane_b32 s30, v254, 38
	v_readlane_b32 s0, v254, 36
	v_cndmask_b32_e32 v171, v162, v163, vcc
	v_cndmask_b32_e32 v170, v164, v165, vcc
	v_lshlrev_b64 v[172:173], 12, v[168:169]
	v_readlane_b32 s31, v254, 39
	v_readlane_b32 s1, v254, 37
	v_lshl_add_u64 v[180:181], v[170:171], 0, v[172:173]
	v_mov_b32_e32 v166, s31
	v_mov_b32_e32 v168, s1
	v_mov_b32_e32 v169, s30
	v_mov_b32_e32 v170, s0
	s_movk_i32 s25, 0x3fff
	v_cndmask_b32_e32 v175, v166, v168, vcc
	v_cndmask_b32_e32 v174, v169, v170, vcc
	v_cmp_lt_i32_e32 vcc, s25, v167
	v_readlane_b32 s0, v253, 63
	v_ashrrev_i32_e32 v161, 31, v160
	v_cndmask_b32_e64 v171, 0, 1, vcc
	v_or_b32_e32 v171, s2, v171
	v_mul_lo_u32 v192, v171, s33
	v_readlane_b32 s1, v254, 0
	v_lshl_add_u64 v[172:173], v[174:175], 0, v[172:173]
	v_lshlrev_b64 v[160:161], 2, v[160:161]
	v_lshl_add_u64 v[174:175], s[0:1], 0, v[192:193]
	v_cndmask_b32_e64 v173, v181, v173, s[38:39]
	v_cndmask_b32_e64 v172, v180, v172, s[38:39]
	v_lshl_add_u64 v[182:183], v[174:175], 0, v[160:161]
	v_lshl_add_u64 v[184:185], v[172:173], 0, v[160:161]
	global_load_dwordx4 v[172:175], v[182:183], off
	global_load_dwordx4 v[176:179], v[184:185], off
	v_lshl_add_u64 v[180:181], v[180:181], 0, v[160:161]
	s_add_i32 s18, s18, 1
	s_waitcnt vmcnt(0)
	v_pk_fma_f32 v[156:157], v[156:157], v[172:173], v[176:177]
	v_pk_fma_f32 v[158:159], v[158:159], v[174:175], v[178:179]
	global_store_dwordx4 v[180:181], v[156:159], off
	global_load_dwordx4 v[156:159], v[182:183], off offset:64
	s_nop 0
	global_load_dwordx4 v[172:175], v[184:185], off offset:64
	s_waitcnt vmcnt(0)
	v_pk_fma_f32 v[152:153], v[152:153], v[156:157], v[172:173]
	v_pk_fma_f32 v[154:155], v[154:155], v[158:159], v[174:175]
	global_store_dwordx4 v[180:181], v[152:155], off offset:64
	global_load_dwordx4 v[152:155], v[182:183], off offset:128
	s_nop 0
	global_load_dwordx4 v[156:159], v[184:185], off offset:128
	s_waitcnt vmcnt(0)
	v_pk_fma_f32 v[148:149], v[148:149], v[152:153], v[156:157]
	v_pk_fma_f32 v[150:151], v[150:151], v[154:155], v[158:159]
	global_store_dwordx4 v[180:181], v[148:151], off offset:128
	global_load_dwordx4 v[148:151], v[182:183], off offset:192
	s_nop 0
	global_load_dwordx4 v[152:155], v[184:185], off offset:192
	v_or_b32_e32 v156, 16, v167
	v_cmp_lt_i32_e32 vcc, s25, v156
	v_add_u32_e32 v158, 0xffffc010, v167
	v_ashrrev_i32_e32 v157, 31, v156
	v_cndmask_b32_e64 v171, 0, 1, vcc
	v_cmp_gt_i32_e32 vcc, s73, v156
	v_or_b32_e32 v171, s2, v171
	v_mul_lo_u32 v192, v171, s33
	v_cndmask_b32_e32 v157, 0, v157, vcc
	v_cndmask_b32_e32 v156, v158, v156, vcc
	v_cndmask_b32_e32 v159, v162, v163, vcc
	v_cndmask_b32_e32 v158, v164, v165, vcc
	v_cndmask_b32_e32 v173, v166, v168, vcc
	v_cndmask_b32_e32 v172, v169, v170, vcc
	v_lshlrev_b64 v[156:157], 12, v[156:157]
	v_lshl_add_u64 v[158:159], v[158:159], 0, v[156:157]
	v_lshl_add_u64 v[156:157], v[172:173], 0, v[156:157]
	v_lshl_add_u64 v[172:173], s[0:1], 0, v[192:193]
	v_cndmask_b32_e64 v157, v159, v157, s[38:39]
	v_cndmask_b32_e64 v156, v158, v156, s[38:39]
	v_lshl_add_u64 v[172:173], v[172:173], 0, v[160:161]
	v_lshl_add_u64 v[156:157], v[156:157], 0, v[160:161]
	s_waitcnt vmcnt(0)
	v_pk_fma_f32 v[144:145], v[144:145], v[148:149], v[152:153]
	v_pk_fma_f32 v[146:147], v[146:147], v[150:151], v[154:155]
	global_store_dwordx4 v[180:181], v[144:147], off offset:192
	global_load_dwordx4 v[144:147], v[172:173], off
	s_nop 0
	global_load_dwordx4 v[148:151], v[156:157], off
	v_lshl_add_u64 v[152:153], v[158:159], 0, v[160:161]
	v_mov_b32_e32 v159, 0
	v_mov_b32_e32 v158, v159
	v_mov_b32_e32 v155, v159
	v_mov_b32_e32 v154, v159
	s_waitcnt vmcnt(0)
	v_pk_fma_f32 v[140:141], v[140:141], v[144:145], v[148:149]
	v_pk_fma_f32 v[142:143], v[142:143], v[146:147], v[150:151]
	global_store_dwordx4 v[152:153], v[140:143], off
	global_load_dwordx4 v[140:143], v[172:173], off offset:64
	s_nop 0
	global_load_dwordx4 v[144:147], v[156:157], off offset:64
	v_mov_b32_e32 v151, v159
	v_mov_b32_e32 v150, v159
	v_mov_b32_e32 v149, v159
	v_mov_b32_e32 v148, v159
	s_waitcnt vmcnt(0)
	v_pk_fma_f32 v[136:137], v[136:137], v[140:141], v[144:145]
	v_pk_fma_f32 v[138:139], v[138:139], v[142:143], v[146:147]
	global_store_dwordx4 v[152:153], v[136:139], off offset:64
	global_load_dwordx4 v[136:139], v[172:173], off offset:128
	s_nop 0
	global_load_dwordx4 v[140:143], v[156:157], off offset:128
	v_mov_b32_e32 v147, v159
	s_waitcnt vmcnt(0)
	v_pk_fma_f32 v[132:133], v[132:133], v[136:137], v[140:141]
	v_pk_fma_f32 v[134:135], v[134:135], v[138:139], v[142:143]
	global_store_dwordx4 v[152:153], v[132:135], off offset:128
	global_load_dwordx4 v[132:135], v[172:173], off offset:192
	s_nop 0
	global_load_dwordx4 v[136:139], v[156:157], off offset:192
	v_or_b32_e32 v140, 32, v167
	v_cmp_lt_i32_e32 vcc, s25, v140
	v_add_u32_e32 v142, 0xffffc020, v167
	v_ashrrev_i32_e32 v141, 31, v140
	v_cndmask_b32_e64 v146, 0, 1, vcc
	v_cmp_gt_i32_e32 vcc, s73, v140
	v_or_b32_e32 v146, s2, v146
	v_mul_lo_u32 v192, v146, s33
	v_cndmask_b32_e32 v141, 0, v141, vcc
	v_cndmask_b32_e32 v140, v142, v140, vcc
	v_cndmask_b32_e32 v143, v162, v163, vcc
	v_cndmask_b32_e32 v142, v164, v165, vcc
	v_cndmask_b32_e32 v145, v166, v168, vcc
	v_cndmask_b32_e32 v144, v169, v170, vcc
	v_lshlrev_b64 v[140:141], 12, v[140:141]
	v_lshl_add_u64 v[142:143], v[142:143], 0, v[140:141]
	v_lshl_add_u64 v[140:141], v[144:145], 0, v[140:141]
	v_lshl_add_u64 v[144:145], s[0:1], 0, v[192:193]
	v_cndmask_b32_e64 v141, v143, v141, s[38:39]
	v_cndmask_b32_e64 v140, v142, v140, s[38:39]
	v_lshl_add_u64 v[144:145], v[144:145], 0, v[160:161]
	v_lshl_add_u64 v[140:141], v[140:141], 0, v[160:161]
	v_mov_b32_e32 v157, v159
	v_mov_b32_e32 v156, v159
	v_mov_b32_e32 v146, v159
	s_waitcnt vmcnt(0)
; template <int MI, int BM, int BN, class ACC>
; DI void resid_epi(const Prm& p, ACC& acc, int row0, int col0, int l, int gchunk, int lane) {
;     ...
;   for (int i = 0; i < MI; ++i) {
;     const int row = row0 + i * 16 + (lane & 15);
;     float* xr = xrow(p, row);
;     const float* xs = (l == 0 && gchunk == 2) ? xrow_in(p, row) : (const float*)xr;
;     const float* gt = mod + (size_t)(l * 2 + (row >= S ? 1 : 0)) * 6144 + gchunk * D;
; #pragma unroll
;     for (int j = 0; j < 4; ++j) {
;       const int col = col0 + j * 16 + 4 * (lane >> 4);
;       const float4 g4 = *(const float4*)(gt + col); float4 xv = *(const float4*)(xs + col);
;       xv.x += g4.x * acc[i][j][0]; xv.y += g4.y * acc[i][j][1]; xv.z += g4.z * acc[i][j][2]; xv.w += g4.w * acc[i][j][3];
;       *(float4*)(xr + col) = xv;
;     }
	v_pk_fma_f32 v[128:129], v[128:129], v[132:133], v[136:137]
	v_pk_fma_f32 v[130:131], v[130:131], v[134:135], v[138:139]
	global_store_dwordx4 v[152:153], v[128:131], off offset:192
	global_load_dwordx4 v[128:131], v[144:145], off
	s_nop 0
	global_load_dwordx4 v[132:135], v[140:141], off
	v_lshl_add_u64 v[136:137], v[142:143], 0, v[160:161]
	v_mov_b32_e32 v153, v159
	v_mov_b32_e32 v152, v159
	v_mov_b32_e32 v143, v159
	v_mov_b32_e32 v142, v159
	v_mov_b32_e32 v139, v159
	v_mov_b32_e32 v138, v159
	s_waitcnt vmcnt(0)
	v_pk_fma_f32 v[124:125], v[124:125], v[128:129], v[132:133]
	v_pk_fma_f32 v[126:127], v[126:127], v[130:131], v[134:135]
	global_store_dwordx4 v[136:137], v[124:127], off
	global_load_dwordx4 v[124:127], v[144:145], off offset:64
	s_nop 0
	global_load_dwordx4 v[128:131], v[140:141], off offset:64
	v_mov_b32_e32 v135, v159
	v_mov_b32_e32 v134, v159
	v_mov_b32_e32 v133, v159
	v_mov_b32_e32 v132, v159
	s_waitcnt vmcnt(0)
	v_pk_fma_f32 v[120:121], v[120:121], v[124:125], v[128:129]
	v_pk_fma_f32 v[122:123], v[122:123], v[126:127], v[130:131]
	global_store_dwordx4 v[136:137], v[120:123], off offset:64
	global_load_dwordx4 v[120:123], v[144:145], off offset:128
	s_nop 0
	global_load_dwordx4 v[124:127], v[140:141], off offset:128
	v_mov_b32_e32 v131, v159
	s_waitcnt vmcnt(0)
	v_pk_fma_f32 v[116:117], v[116:117], v[120:121], v[124:125]
	v_pk_fma_f32 v[118:119], v[118:119], v[122:123], v[126:127]
	global_store_dwordx4 v[136:137], v[116:119], off offset:128
	global_load_dwordx4 v[116:119], v[144:145], off offset:192
	s_nop 0
	global_load_dwordx4 v[120:123], v[140:141], off offset:192
	v_or_b32_e32 v124, 48, v167
	v_cmp_lt_i32_e32 vcc, s25, v124
	v_add_u32_e32 v126, 0xffffc030, v167
	v_ashrrev_i32_e32 v125, 31, v124
	v_cndmask_b32_e64 v130, 0, 1, vcc
	v_cmp_gt_i32_e32 vcc, s73, v124
	v_or_b32_e32 v130, s2, v130
	v_mul_lo_u32 v192, v130, s33
	v_cndmask_b32_e32 v125, 0, v125, vcc
	v_cndmask_b32_e32 v124, v126, v124, vcc
	v_cndmask_b32_e32 v127, v162, v163, vcc
	v_cndmask_b32_e32 v126, v164, v165, vcc
	v_cndmask_b32_e32 v129, v166, v168, vcc
	v_cndmask_b32_e32 v128, v169, v170, vcc
	v_lshlrev_b64 v[124:125], 12, v[124:125]
	v_lshl_add_u64 v[126:127], v[126:127], 0, v[124:125]
	v_lshl_add_u64 v[124:125], v[128:129], 0, v[124:125]
	v_lshl_add_u64 v[128:129], s[0:1], 0, v[192:193]
	v_cndmask_b32_e64 v125, v127, v125, s[38:39]
	v_cndmask_b32_e64 v124, v126, v124, s[38:39]
	v_lshl_add_u64 v[128:129], v[128:129], 0, v[160:161]
	v_lshl_add_u64 v[124:125], v[124:125], 0, v[160:161]
	v_mov_b32_e32 v145, v159
	v_mov_b32_e32 v144, v159
	v_mov_b32_e32 v141, v159
	v_mov_b32_e32 v140, v159
	v_mov_b32_e32 v130, v159
	s_waitcnt vmcnt(0)
	v_pk_fma_f32 v[112:113], v[112:113], v[116:117], v[120:121]
	v_pk_fma_f32 v[114:115], v[114:115], v[118:119], v[122:123]
	global_store_dwordx4 v[136:137], v[112:115], off offset:192
	global_load_dwordx4 v[152:155], v[128:129], off
	global_load_dwordx4 v[148:151], v[124:125], off
	global_load_dwordx4 v[144:147], v[128:129], off offset:64
	global_load_dwordx4 v[140:143], v[124:125], off offset:64
	s_nop 0
	v_lshl_add_u64 v[120:121], v[126:127], 0, v[160:161]
	v_mov_b32_e32 v137, v159
	v_mov_b32_e32 v136, v159
	v_mov_b32_e32 v127, v159
	v_mov_b32_e32 v126, v159
	v_mov_b32_e32 v123, v159
	v_mov_b32_e32 v122, v159
	s_waitcnt vmcnt(2)
	v_pk_fma_f32 v[108:109], v[108:109], v[152:153], v[148:149]
	v_pk_fma_f32 v[110:111], v[110:111], v[154:155], v[150:151]
	global_store_dwordx4 v[120:121], v[108:111], off
	s_nop 0
	v_mov_b32_e32 v119, v159
	v_mov_b32_e32 v118, v159
	v_mov_b32_e32 v117, v159
	v_mov_b32_e32 v116, v159
	s_waitcnt vmcnt(1)
	v_pk_fma_f32 v[104:105], v[104:105], v[144:145], v[140:141]
	v_pk_fma_f32 v[106:107], v[106:107], v[146:147], v[142:143]
	global_store_dwordx4 v[120:121], v[104:107], off offset:64
	global_load_dwordx4 v[152:155], v[128:129], off offset:128
	global_load_dwordx4 v[148:151], v[124:125], off offset:128
	global_load_dwordx4 v[144:147], v[128:129], off offset:192
	global_load_dwordx4 v[140:143], v[124:125], off offset:192
	s_nop 0
	v_mov_b32_e32 v115, v159
	s_waitcnt vmcnt(2)
	v_pk_fma_f32 v[100:101], v[100:101], v[152:153], v[148:149]
	v_pk_fma_f32 v[102:103], v[102:103], v[154:155], v[150:151]
	global_store_dwordx4 v[120:121], v[100:103], off offset:128
	s_nop 0
	v_or_b32_e32 v108, 64, v167
	v_cmp_lt_i32_e32 vcc, s25, v108
	v_add_u32_e32 v110, 0xffffc040, v167
	v_ashrrev_i32_e32 v109, 31, v108
	v_cndmask_b32_e64 v114, 0, 1, vcc
	v_cmp_gt_i32_e32 vcc, s73, v108
	v_or_b32_e32 v114, s2, v114
	v_mul_lo_u32 v192, v114, s33
	v_cndmask_b32_e32 v109, 0, v109, vcc
	v_cndmask_b32_e32 v108, v110, v108, vcc
	v_cndmask_b32_e32 v111, v162, v163, vcc
	v_cndmask_b32_e32 v110, v164, v165, vcc
	v_cndmask_b32_e32 v113, v166, v168, vcc
	v_cndmask_b32_e32 v112, v169, v170, vcc
	v_lshlrev_b64 v[108:109], 12, v[108:109]
	v_lshl_add_u64 v[110:111], v[110:111], 0, v[108:109]
	v_lshl_add_u64 v[108:109], v[112:113], 0, v[108:109]
	v_lshl_add_u64 v[112:113], s[0:1], 0, v[192:193]
	v_cndmask_b32_e64 v109, v111, v109, s[38:39]
	v_cndmask_b32_e64 v108, v110, v108, s[38:39]
	v_lshl_add_u64 v[112:113], v[112:113], 0, v[160:161]
	v_lshl_add_u64 v[108:109], v[108:109], 0, v[160:161]
	v_mov_b32_e32 v129, v159
	v_mov_b32_e32 v128, v159
	v_mov_b32_e32 v125, v159
	v_mov_b32_e32 v124, v159
	v_mov_b32_e32 v114, v159
	s_waitcnt vmcnt(1)
; template <int MI, int BM, int BN, class ACC>
; DI void resid_epi(const Prm& p, ACC& acc, int row0, int col0, int l, int gchunk, int lane) {
;     ...
;   for (int i = 0; i < MI; ++i) {
;     const int row = row0 + i * 16 + (lane & 15);
;     float* xr = xrow(p, row);
;     const float* xs = (l == 0 && gchunk == 2) ? xrow_in(p, row) : (const float*)xr;
;     const float* gt = mod + (size_t)(l * 2 + (row >= S ? 1 : 0)) * 6144 + gchunk * D;
; #pragma unroll
;     for (int j = 0; j < 4; ++j) {
;       const int col = col0 + j * 16 + 4 * (lane >> 4);
;       const float4 g4 = *(const float4*)(gt + col); float4 xv = *(const float4*)(xs + col);
;       xv.x += g4.x * acc[i][j][0]; xv.y += g4.y * acc[i][j][1]; xv.z += g4.z * acc[i][j][2]; xv.w += g4.w * acc[i][j][3];
;       *(float4*)(xr + col) = xv;
;     }
	v_pk_fma_f32 v[96:97], v[96:97], v[144:145], v[140:141]
	v_pk_fma_f32 v[98:99], v[98:99], v[146:147], v[142:143]
	global_store_dwordx4 v[120:121], v[96:99], off offset:192
	global_load_dwordx4 v[152:155], v[112:113], off
	global_load_dwordx4 v[148:151], v[108:109], off
	global_load_dwordx4 v[144:147], v[112:113], off offset:64
	global_load_dwordx4 v[140:143], v[108:109], off offset:64
	global_load_dwordx4 v[136:139], v[112:113], off offset:128
	global_load_dwordx4 v[132:135], v[108:109], off offset:128
	global_load_dwordx4 v[128:131], v[112:113], off offset:192
	global_load_dwordx4 v[124:127], v[108:109], off offset:192
	s_nop 0
	v_lshl_add_u64 v[104:105], v[110:111], 0, v[160:161]
	v_mov_b32_e32 v121, v159
	v_mov_b32_e32 v120, v159
	v_mov_b32_e32 v111, v159
	v_mov_b32_e32 v110, v159
	v_mov_b32_e32 v107, v159
	v_mov_b32_e32 v106, v159
	s_waitcnt vmcnt(6)
	v_pk_fma_f32 v[92:93], v[92:93], v[152:153], v[148:149]
	v_pk_fma_f32 v[94:95], v[94:95], v[154:155], v[150:151]
	global_store_dwordx4 v[104:105], v[92:95], off
	s_nop 0
	v_mov_b32_e32 v103, v159
	v_mov_b32_e32 v102, v159
	v_mov_b32_e32 v101, v159
	v_mov_b32_e32 v100, v159
	s_waitcnt vmcnt(5)
	v_pk_fma_f32 v[88:89], v[88:89], v[144:145], v[140:141]
	v_pk_fma_f32 v[90:91], v[90:91], v[146:147], v[142:143]
	global_store_dwordx4 v[104:105], v[88:91], off offset:64
	s_nop 0
	v_mov_b32_e32 v99, v159
	s_waitcnt vmcnt(4)
	v_pk_fma_f32 v[84:85], v[84:85], v[136:137], v[132:133]
	v_pk_fma_f32 v[86:87], v[86:87], v[138:139], v[134:135]
	global_store_dwordx4 v[104:105], v[84:87], off offset:128
	s_nop 0
	v_or_b32_e32 v92, 0x50, v167
	v_cmp_lt_i32_e32 vcc, s25, v92
	v_add_u32_e32 v94, 0xffffc050, v167
	v_ashrrev_i32_e32 v93, 31, v92
	v_cndmask_b32_e64 v98, 0, 1, vcc
	v_cmp_gt_i32_e32 vcc, s73, v92
	v_or_b32_e32 v98, s2, v98
	v_mul_lo_u32 v192, v98, s33
	v_cndmask_b32_e32 v93, 0, v93, vcc
	v_cndmask_b32_e32 v92, v94, v92, vcc
	v_cndmask_b32_e32 v95, v162, v163, vcc
	v_cndmask_b32_e32 v94, v164, v165, vcc
	v_cndmask_b32_e32 v97, v166, v168, vcc
	v_cndmask_b32_e32 v96, v169, v170, vcc
	v_lshlrev_b64 v[92:93], 12, v[92:93]
	v_lshl_add_u64 v[94:95], v[94:95], 0, v[92:93]
	v_lshl_add_u64 v[92:93], v[96:97], 0, v[92:93]
	v_lshl_add_u64 v[96:97], s[0:1], 0, v[192:193]
	v_cndmask_b32_e64 v93, v95, v93, s[38:39]
	v_cndmask_b32_e64 v92, v94, v92, s[38:39]
	v_lshl_add_u64 v[96:97], v[96:97], 0, v[160:161]
	v_lshl_add_u64 v[92:93], v[92:93], 0, v[160:161]
	v_mov_b32_e32 v113, v159
	v_mov_b32_e32 v112, v159
	v_mov_b32_e32 v109, v159
	v_mov_b32_e32 v108, v159
	v_mov_b32_e32 v98, v159
	s_waitcnt vmcnt(3)
	v_pk_fma_f32 v[80:81], v[80:81], v[128:129], v[124:125]
	v_pk_fma_f32 v[82:83], v[82:83], v[130:131], v[126:127]
	global_store_dwordx4 v[104:105], v[80:83], off offset:192
	global_load_dwordx4 v[152:155], v[96:97], off
	global_load_dwordx4 v[148:151], v[92:93], off
	global_load_dwordx4 v[144:147], v[96:97], off offset:64
	global_load_dwordx4 v[140:143], v[92:93], off offset:64
	global_load_dwordx4 v[136:139], v[96:97], off offset:128
	global_load_dwordx4 v[132:135], v[92:93], off offset:128
	global_load_dwordx4 v[128:131], v[96:97], off offset:192
	global_load_dwordx4 v[124:127], v[92:93], off offset:192
	s_nop 0
	v_lshl_add_u64 v[88:89], v[94:95], 0, v[160:161]
	v_mov_b32_e32 v105, v159
	v_mov_b32_e32 v104, v159
	v_mov_b32_e32 v95, v159
	v_mov_b32_e32 v94, v159
	v_mov_b32_e32 v91, v159
	v_mov_b32_e32 v90, v159
	s_waitcnt vmcnt(6)
	v_pk_fma_f32 v[76:77], v[76:77], v[152:153], v[148:149]
	v_pk_fma_f32 v[78:79], v[78:79], v[154:155], v[150:151]
	global_store_dwordx4 v[88:89], v[76:79], off
	s_nop 0
	v_mov_b32_e32 v87, v159
	v_mov_b32_e32 v86, v159
	v_mov_b32_e32 v85, v159
	v_mov_b32_e32 v84, v159
	s_waitcnt vmcnt(5)
	v_pk_fma_f32 v[72:73], v[72:73], v[144:145], v[140:141]
	v_pk_fma_f32 v[74:75], v[74:75], v[146:147], v[142:143]
	global_store_dwordx4 v[88:89], v[72:75], off offset:64
	s_nop 0
	v_mov_b32_e32 v83, v159
	s_waitcnt vmcnt(4)
	v_pk_fma_f32 v[68:69], v[68:69], v[136:137], v[132:133]
	v_pk_fma_f32 v[70:71], v[70:71], v[138:139], v[134:135]
	global_store_dwordx4 v[88:89], v[68:71], off offset:128
	s_nop 0
	v_or_b32_e32 v76, 0x60, v167
	v_cmp_lt_i32_e32 vcc, s25, v76
	v_add_u32_e32 v78, 0xffffc060, v167
	v_ashrrev_i32_e32 v77, 31, v76
	v_cndmask_b32_e64 v82, 0, 1, vcc
	v_cmp_gt_i32_e32 vcc, s73, v76
	v_or_b32_e32 v82, s2, v82
	v_mul_lo_u32 v192, v82, s33
	v_cndmask_b32_e32 v77, 0, v77, vcc
	v_cndmask_b32_e32 v76, v78, v76, vcc
	v_cndmask_b32_e32 v79, v162, v163, vcc
	v_cndmask_b32_e32 v78, v164, v165, vcc
	v_cndmask_b32_e32 v81, v166, v168, vcc
	v_cndmask_b32_e32 v80, v169, v170, vcc
	v_lshlrev_b64 v[76:77], 12, v[76:77]
	v_lshl_add_u64 v[78:79], v[78:79], 0, v[76:77]
	v_lshl_add_u64 v[76:77], v[80:81], 0, v[76:77]
	v_lshl_add_u64 v[80:81], s[0:1], 0, v[192:193]
	v_cndmask_b32_e64 v77, v79, v77, s[38:39]
	v_cndmask_b32_e64 v76, v78, v76, s[38:39]
	v_lshl_add_u64 v[80:81], v[80:81], 0, v[160:161]
	v_lshl_add_u64 v[76:77], v[76:77], 0, v[160:161]
	v_mov_b32_e32 v97, v159
	v_mov_b32_e32 v96, v159
	v_mov_b32_e32 v93, v159
	v_mov_b32_e32 v92, v159
	v_mov_b32_e32 v82, v159
	s_waitcnt vmcnt(3)
; template <int MI, int BM, int BN, class ACC>
; DI void resid_epi(const Prm& p, ACC& acc, int row0, int col0, int l, int gchunk, int lane) {
;     ...
;   for (int i = 0; i < MI; ++i) {
;     const int row = row0 + i * 16 + (lane & 15);
;     float* xr = xrow(p, row);
;     const float* xs = (l == 0 && gchunk == 2) ? xrow_in(p, row) : (const float*)xr;
;     const float* gt = mod + (size_t)(l * 2 + (row >= S ? 1 : 0)) * 6144 + gchunk * D;
; #pragma unroll
;     for (int j = 0; j < 4; ++j) {
;       const int col = col0 + j * 16 + 4 * (lane >> 4);
;       const float4 g4 = *(const float4*)(gt + col); float4 xv = *(const float4*)(xs + col);
;       xv.x += g4.x * acc[i][j][0]; xv.y += g4.y * acc[i][j][1]; xv.z += g4.z * acc[i][j][2]; xv.w += g4.w * acc[i][j][3];
;       *(float4*)(xr + col) = xv;
;     }
	v_pk_fma_f32 v[64:65], v[64:65], v[128:129], v[124:125]
	v_pk_fma_f32 v[66:67], v[66:67], v[130:131], v[126:127]
	global_store_dwordx4 v[88:89], v[64:67], off offset:192
	global_load_dwordx4 v[152:155], v[80:81], off
	global_load_dwordx4 v[148:151], v[76:77], off
	global_load_dwordx4 v[144:147], v[80:81], off offset:64
	global_load_dwordx4 v[140:143], v[76:77], off offset:64
	global_load_dwordx4 v[136:139], v[80:81], off offset:128
	global_load_dwordx4 v[132:135], v[76:77], off offset:128
	global_load_dwordx4 v[128:131], v[80:81], off offset:192
	global_load_dwordx4 v[124:127], v[76:77], off offset:192
	s_nop 0
	v_lshl_add_u64 v[72:73], v[78:79], 0, v[160:161]
	v_mov_b32_e32 v89, v159
	v_mov_b32_e32 v88, v159
	v_mov_b32_e32 v79, v159
	v_mov_b32_e32 v78, v159
	v_mov_b32_e32 v75, v159
	v_mov_b32_e32 v74, v159
	s_waitcnt vmcnt(6)
	v_pk_fma_f32 v[60:61], v[60:61], v[152:153], v[148:149]
	v_pk_fma_f32 v[62:63], v[62:63], v[154:155], v[150:151]
	global_store_dwordx4 v[72:73], v[60:63], off
	s_nop 0
	v_mov_b32_e32 v71, v159
	v_mov_b32_e32 v70, v159
	v_mov_b32_e32 v69, v159
	v_mov_b32_e32 v68, v159
	s_waitcnt vmcnt(5)
	v_pk_fma_f32 v[56:57], v[56:57], v[144:145], v[140:141]
	v_pk_fma_f32 v[58:59], v[58:59], v[146:147], v[142:143]
	global_store_dwordx4 v[72:73], v[56:59], off offset:64
	s_nop 0
	v_mov_b32_e32 v67, v159
	s_waitcnt vmcnt(4)
	v_pk_fma_f32 v[52:53], v[52:53], v[136:137], v[132:133]
	v_pk_fma_f32 v[54:55], v[54:55], v[138:139], v[134:135]
	global_store_dwordx4 v[72:73], v[52:55], off offset:128
	s_nop 0
	v_or_b32_e32 v60, 0x70, v167
	v_cmp_lt_i32_e32 vcc, s25, v60
	v_add_u32_e32 v62, 0xffffc070, v167
	v_ashrrev_i32_e32 v61, 31, v60
	v_cndmask_b32_e64 v66, 0, 1, vcc
	v_cmp_gt_i32_e32 vcc, s73, v60
	v_or_b32_e32 v66, s2, v66
	v_mul_lo_u32 v192, v66, s33
	v_cndmask_b32_e32 v61, 0, v61, vcc
	v_cndmask_b32_e32 v60, v62, v60, vcc
	v_cndmask_b32_e32 v63, v162, v163, vcc
	v_cndmask_b32_e32 v62, v164, v165, vcc
	v_cndmask_b32_e32 v65, v166, v168, vcc
	v_cndmask_b32_e32 v64, v169, v170, vcc
	v_lshlrev_b64 v[60:61], 12, v[60:61]
	v_lshl_add_u64 v[62:63], v[62:63], 0, v[60:61]
	v_lshl_add_u64 v[60:61], v[64:65], 0, v[60:61]
	v_lshl_add_u64 v[64:65], s[0:1], 0, v[192:193]
	v_cndmask_b32_e64 v61, v63, v61, s[38:39]
	v_cndmask_b32_e64 v60, v62, v60, s[38:39]
	v_lshl_add_u64 v[64:65], v[64:65], 0, v[160:161]
	v_lshl_add_u64 v[60:61], v[60:61], 0, v[160:161]
	v_lshl_add_u64 v[168:169], v[62:63], 0, v[160:161]
	s_mov_b32 s25, 0
	v_mov_b32_e32 v81, v159
	v_mov_b32_e32 v80, v159
	v_mov_b32_e32 v77, v159
	v_mov_b32_e32 v76, v159
	v_mov_b32_e32 v66, v159
	v_mov_b32_e32 v63, v159
	v_mov_b32_e32 v62, v159
	s_waitcnt vmcnt(3)
	v_pk_fma_f32 v[48:49], v[48:49], v[128:129], v[124:125]
	v_pk_fma_f32 v[50:51], v[50:51], v[130:131], v[126:127]
	global_store_dwordx4 v[72:73], v[48:51], off offset:192
	global_load_dwordx4 v[152:155], v[64:65], off
	global_load_dwordx4 v[148:151], v[60:61], off
	global_load_dwordx4 v[144:147], v[64:65], off offset:64
	global_load_dwordx4 v[140:143], v[60:61], off offset:64
	global_load_dwordx4 v[136:139], v[64:65], off offset:128
	global_load_dwordx4 v[132:135], v[60:61], off offset:128
	global_load_dwordx4 v[128:131], v[64:65], off offset:192
	global_load_dwordx4 v[124:127], v[60:61], off offset:192
	s_nop 0
	v_mov_b32_e32 v73, v159
	v_mov_b32_e32 v72, v159
	v_mov_b32_e32 v59, v159
	v_mov_b32_e32 v58, v159
	v_mov_b32_e32 v57, v159
	v_mov_b32_e32 v56, v159
	s_waitcnt vmcnt(6)
	v_pk_fma_f32 v[44:45], v[44:45], v[152:153], v[148:149]
	v_pk_fma_f32 v[46:47], v[46:47], v[154:155], v[150:151]
	global_store_dwordx4 v[168:169], v[44:47], off
	s_nop 0
	v_mov_b32_e32 v55, v159
	v_mov_b32_e32 v54, v159
	v_mov_b32_e32 v53, v159
	v_mov_b32_e32 v52, v159
	s_waitcnt vmcnt(5)
	v_pk_fma_f32 v[40:41], v[40:41], v[144:145], v[140:141]
	v_pk_fma_f32 v[42:43], v[42:43], v[146:147], v[142:143]
	global_store_dwordx4 v[168:169], v[40:43], off offset:64
	s_nop 0
	v_mov_b32_e32 v51, v159
	v_mov_b32_e32 v50, v159
	v_mov_b32_e32 v49, v159
	v_mov_b32_e32 v48, v159
	s_waitcnt vmcnt(4)
	v_pk_fma_f32 v[36:37], v[36:37], v[136:137], v[132:133]
	v_pk_fma_f32 v[38:39], v[38:39], v[138:139], v[134:135]
	global_store_dwordx4 v[168:169], v[36:39], off offset:128
	v_mov_b32_e32 v65, v159
	v_mov_b32_e32 v64, v159
	v_mov_b32_e32 v61, v159
	v_mov_b32_e32 v60, v159
	v_mov_b32_e32 v47, v159
	v_mov_b32_e32 v46, v159
	v_mov_b32_e32 v45, v159
	v_mov_b32_e32 v44, v159
	v_mov_b32_e32 v43, v159
	v_mov_b32_e32 v42, v159
	v_mov_b32_e32 v41, v159
	v_mov_b32_e32 v40, v159
	v_mov_b32_e32 v39, v159
	v_mov_b32_e32 v38, v159
	v_mov_b32_e32 v37, v159
	v_mov_b32_e32 v36, v159
	s_waitcnt vmcnt(3)
	v_pk_fma_f32 v[128:129], v[8:9], v[128:129], v[124:125]
	v_pk_fma_f32 v[130:131], v[10:11], v[130:131], v[126:127]
	v_mov_b32_e32 v11, v159
	v_mov_b32_e32 v10, v159
	v_mov_b32_e32 v9, v159
	v_mov_b32_e32 v8, v159
	global_store_dwordx4 v[168:169], v[128:131], off offset:192
	s_nop 1
	v_mov_b32_e32 v124, v159
	v_mov_b32_e32 v125, v159
	v_mov_b32_e32 v126, v159
	v_mov_b32_e32 v127, v159
	v_mov_b32_e32 v128, v159
	v_mov_b32_e32 v129, v159
	v_mov_b32_e32 v130, v159
	v_mov_b32_e32 v131, v159
	v_mov_b32_e32 v132, v159
	v_mov_b32_e32 v133, v159
	v_mov_b32_e32 v134, v159
	v_mov_b32_e32 v135, v159
	v_mov_b32_e32 v136, v159
	v_mov_b32_e32 v137, v159
	v_mov_b32_e32 v138, v159
	v_mov_b32_e32 v139, v159
	v_mov_b32_e32 v140, v159
	v_mov_b32_e32 v141, v159
	v_mov_b32_e32 v142, v159
	v_mov_b32_e32 v143, v159
	v_mov_b32_e32 v144, v159
	v_mov_b32_e32 v145, v159
	v_mov_b32_e32 v146, v159
	v_mov_b32_e32 v147, v159
	v_mov_b32_e32 v148, v159
	v_mov_b32_e32 v149, v159
	v_mov_b32_e32 v150, v159
	v_mov_b32_e32 v151, v159
	v_mov_b32_e32 v152, v159
	v_mov_b32_e32 v153, v159
	v_mov_b32_e32 v154, v159
	v_mov_b32_e32 v155, v159

; template <int MI, int BM, int BN, class ACC>
; DI void resid_epi(const Prm& p, ACC& acc, int row0, int col0, int l, int gchunk, int lane) {
;     ...
;   for (int i = 0; i < MI; ++i) {
;     const int row = row0 + i * 16 + (lane & 15);
;     float* xr = xrow(p, row);
;     const float* xs = (l == 0 && gchunk == 2) ? xrow_in(p, row) : (const float*)xr;
;     const float* gt = mod + (size_t)(l * 2 + (row >= S ? 1 : 0)) * 6144 + gchunk * D;
; #pragma unroll
;     for (int j = 0; j < 4; ++j) {
;       const int col = col0 + j * 16 + 4 * (lane >> 4);
;       const float4 g4 = *(const float4*)(gt + col); float4 xv = *(const float4*)(xs + col);
;       xv.x += g4.x * acc[i][j][0]; xv.y += g4.y * acc[i][j][1]; xv.z += g4.z * acc[i][j][2]; xv.w += g4.w * acc[i][j][3];
;       *(float4*)(xr + col) = xv;
;     }
.LBB0_1668:
	v_lshl_add_u32 v167, s41, 8, v238
	v_add_u32_e32 v162, 0xffffc000, v167
	v_cmp_gt_i32_e32 vcc, s73, v167
	v_readlane_b32 s0, v253, 58
	v_ashrrev_i32_e32 v163, 31, v167
	v_cndmask_b32_e32 v168, v162, v167, vcc
	v_mov_b32_e32 v162, s0
	v_readlane_b32 s0, v253, 57
	v_cndmask_b32_e32 v169, 0, v163, vcc
	v_mov_b32_e32 v163, s65
	v_mov_b32_e32 v164, s0
	v_mov_b32_e32 v165, s64
	v_readlane_b32 s40, v254, 38
	v_readlane_b32 s0, v254, 36
	v_cndmask_b32_e32 v171, v162, v163, vcc
	v_cndmask_b32_e32 v170, v164, v165, vcc
	v_lshlrev_b64 v[172:173], 12, v[168:169]
	v_readlane_b32 s41, v254, 39
	v_readlane_b32 s1, v254, 37
	v_lshl_add_u64 v[180:181], v[170:171], 0, v[172:173]
	v_mov_b32_e32 v166, s41
	v_mov_b32_e32 v168, s1
	v_mov_b32_e32 v169, s40
	v_mov_b32_e32 v170, s0
	s_movk_i32 s40, 0x3fff
	v_cndmask_b32_e32 v175, v166, v168, vcc
	v_cndmask_b32_e32 v174, v169, v170, vcc
	v_cmp_lt_i32_e32 vcc, s40, v167
	v_lshl_add_u32 v160, s42, 8, v239
	v_readlane_b32 s0, v253, 63
	v_cndmask_b32_e64 v171, 0, 1, vcc
	v_or_b32_e32 v171, s2, v171
	v_ashrrev_i32_e32 v161, 31, v160
	v_mul_lo_u32 v192, v171, s33
	v_readlane_b32 s1, v254, 0
	v_lshl_add_u64 v[172:173], v[174:175], 0, v[172:173]
	v_lshlrev_b64 v[160:161], 2, v[160:161]
	v_lshl_add_u64 v[174:175], s[0:1], 0, v[192:193]
	v_cndmask_b32_e64 v173, v181, v173, s[38:39]
	v_cndmask_b32_e64 v172, v180, v172, s[38:39]
	v_lshl_add_u64 v[182:183], v[174:175], 0, v[160:161]
	v_lshl_add_u64 v[184:185], v[172:173], 0, v[160:161]
	global_load_dwordx4 v[172:175], v[182:183], off
	global_load_dwordx4 v[176:179], v[184:185], off
	v_lshl_add_u64 v[180:181], v[180:181], 0, v[160:161]
	s_add_i32 s25, s25, 1
	s_waitcnt vmcnt(0)
	v_pk_fma_f32 v[156:157], v[156:157], v[172:173], v[176:177]
	v_pk_fma_f32 v[158:159], v[158:159], v[174:175], v[178:179]
	global_store_dwordx4 v[180:181], v[156:159], off
	global_load_dwordx4 v[156:159], v[182:183], off offset:64
	s_nop 0
	global_load_dwordx4 v[172:175], v[184:185], off offset:64
	s_waitcnt vmcnt(0)
	v_pk_fma_f32 v[152:153], v[152:153], v[156:157], v[172:173]
	v_pk_fma_f32 v[154:155], v[154:155], v[158:159], v[174:175]
	global_store_dwordx4 v[180:181], v[152:155], off offset:64
	global_load_dwordx4 v[152:155], v[182:183], off offset:128
	s_nop 0
	global_load_dwordx4 v[156:159], v[184:185], off offset:128
	s_waitcnt vmcnt(0)
	v_pk_fma_f32 v[148:149], v[148:149], v[152:153], v[156:157]
	v_pk_fma_f32 v[150:151], v[150:151], v[154:155], v[158:159]
	global_store_dwordx4 v[180:181], v[148:151], off offset:128
	global_load_dwordx4 v[148:151], v[182:183], off offset:192
	s_nop 0
	global_load_dwordx4 v[152:155], v[184:185], off offset:192
	v_or_b32_e32 v156, 16, v167
	v_cmp_lt_i32_e32 vcc, s40, v156
	v_add_u32_e32 v158, 0xffffc010, v167
	v_ashrrev_i32_e32 v157, 31, v156
	v_cndmask_b32_e64 v171, 0, 1, vcc
	v_cmp_gt_i32_e32 vcc, s73, v156
	v_or_b32_e32 v171, s2, v171
	v_mul_lo_u32 v192, v171, s33
	v_cndmask_b32_e32 v157, 0, v157, vcc
	v_cndmask_b32_e32 v156, v158, v156, vcc
	v_cndmask_b32_e32 v159, v162, v163, vcc
	v_cndmask_b32_e32 v158, v164, v165, vcc
	v_cndmask_b32_e32 v173, v166, v168, vcc
	v_cndmask_b32_e32 v172, v169, v170, vcc
	v_lshlrev_b64 v[156:157], 12, v[156:157]
	v_lshl_add_u64 v[158:159], v[158:159], 0, v[156:157]
	v_lshl_add_u64 v[156:157], v[172:173], 0, v[156:157]
	v_lshl_add_u64 v[172:173], s[0:1], 0, v[192:193]
	v_cndmask_b32_e64 v157, v159, v157, s[38:39]
	v_cndmask_b32_e64 v156, v158, v156, s[38:39]
	v_lshl_add_u64 v[172:173], v[172:173], 0, v[160:161]
	v_lshl_add_u64 v[156:157], v[156:157], 0, v[160:161]
	s_waitcnt vmcnt(0)
	v_pk_fma_f32 v[144:145], v[144:145], v[148:149], v[152:153]
	v_pk_fma_f32 v[146:147], v[146:147], v[150:151], v[154:155]
	global_store_dwordx4 v[180:181], v[144:147], off offset:192
	global_load_dwordx4 v[144:147], v[172:173], off
	s_nop 0
	global_load_dwordx4 v[148:151], v[156:157], off
	v_lshl_add_u64 v[152:153], v[158:159], 0, v[160:161]
	v_mov_b32_e32 v159, 0
	v_mov_b32_e32 v158, v159
	v_mov_b32_e32 v155, v159
	v_mov_b32_e32 v154, v159
	s_waitcnt vmcnt(0)
	v_pk_fma_f32 v[140:141], v[140:141], v[144:145], v[148:149]
	v_pk_fma_f32 v[142:143], v[142:143], v[146:147], v[150:151]
	global_store_dwordx4 v[152:153], v[140:143], off
	global_load_dwordx4 v[140:143], v[172:173], off offset:64
	s_nop 0
	global_load_dwordx4 v[144:147], v[156:157], off offset:64
	v_mov_b32_e32 v151, v159
	v_mov_b32_e32 v150, v159
	v_mov_b32_e32 v149, v159
	v_mov_b32_e32 v148, v159
	s_waitcnt vmcnt(0)
	v_pk_fma_f32 v[136:137], v[136:137], v[140:141], v[144:145]
	v_pk_fma_f32 v[138:139], v[138:139], v[142:143], v[146:147]
	global_store_dwordx4 v[152:153], v[136:139], off offset:64
	global_load_dwordx4 v[136:139], v[172:173], off offset:128
	s_nop 0
	global_load_dwordx4 v[140:143], v[156:157], off offset:128
	v_mov_b32_e32 v147, v159
	s_waitcnt vmcnt(0)
	v_pk_fma_f32 v[132:133], v[132:133], v[136:137], v[140:141]
	v_pk_fma_f32 v[134:135], v[134:135], v[138:139], v[142:143]
	global_store_dwordx4 v[152:153], v[132:135], off offset:128
	global_load_dwordx4 v[132:135], v[172:173], off offset:192
	s_nop 0
	global_load_dwordx4 v[136:139], v[156:157], off offset:192
	v_or_b32_e32 v140, 32, v167
	v_cmp_lt_i32_e32 vcc, s40, v140
	v_add_u32_e32 v142, 0xffffc020, v167
	v_ashrrev_i32_e32 v141, 31, v140
	v_cndmask_b32_e64 v146, 0, 1, vcc
	v_cmp_gt_i32_e32 vcc, s73, v140
	v_or_b32_e32 v146, s2, v146
	v_mul_lo_u32 v192, v146, s33
	v_cndmask_b32_e32 v141, 0, v141, vcc
	v_cndmask_b32_e32 v140, v142, v140, vcc
	v_cndmask_b32_e32 v143, v162, v163, vcc
	v_cndmask_b32_e32 v142, v164, v165, vcc
	v_cndmask_b32_e32 v145, v166, v168, vcc
	v_cndmask_b32_e32 v144, v169, v170, vcc
	v_lshlrev_b64 v[140:141], 12, v[140:141]
	v_lshl_add_u64 v[142:143], v[142:143], 0, v[140:141]
	v_lshl_add_u64 v[140:141], v[144:145], 0, v[140:141]
	v_lshl_add_u64 v[144:145], s[0:1], 0, v[192:193]
	v_cndmask_b32_e64 v141, v143, v141, s[38:39]
	v_cndmask_b32_e64 v140, v142, v140, s[38:39]
	v_lshl_add_u64 v[144:145], v[144:145], 0, v[160:161]
	v_lshl_add_u64 v[140:141], v[140:141], 0, v[160:161]
	v_mov_b32_e32 v157, v159
	v_mov_b32_e32 v156, v159
	v_mov_b32_e32 v146, v159
	s_waitcnt vmcnt(0)
; template <int MI, int BM, int BN, class ACC>
; DI void resid_epi(const Prm& p, ACC& acc, int row0, int col0, int l, int gchunk, int lane) {
;     ...
;   for (int i = 0; i < MI; ++i) {
;     const int row = row0 + i * 16 + (lane & 15);
;     float* xr = xrow(p, row);
;     const float* xs = (l == 0 && gchunk == 2) ? xrow_in(p, row) : (const float*)xr;
;     const float* gt = mod + (size_t)(l * 2 + (row >= S ? 1 : 0)) * 6144 + gchunk * D;
; #pragma unroll
;     for (int j = 0; j < 4; ++j) {
;       const int col = col0 + j * 16 + 4 * (lane >> 4);
;       const float4 g4 = *(const float4*)(gt + col); float4 xv = *(const float4*)(xs + col);
;       xv.x += g4.x * acc[i][j][0]; xv.y += g4.y * acc[i][j][1]; xv.z += g4.z * acc[i][j][2]; xv.w += g4.w * acc[i][j][3];
;       *(float4*)(xr + col) = xv;
;     }
	v_pk_fma_f32 v[128:129], v[128:129], v[132:133], v[136:137]
	v_pk_fma_f32 v[130:131], v[130:131], v[134:135], v[138:139]
	global_store_dwordx4 v[152:153], v[128:131], off offset:192
	global_load_dwordx4 v[128:131], v[144:145], off
	s_nop 0
	global_load_dwordx4 v[132:135], v[140:141], off
	v_lshl_add_u64 v[136:137], v[142:143], 0, v[160:161]
	v_mov_b32_e32 v153, v159
	v_mov_b32_e32 v152, v159
	v_mov_b32_e32 v143, v159
	v_mov_b32_e32 v142, v159
	v_mov_b32_e32 v139, v159
	v_mov_b32_e32 v138, v159
	s_waitcnt vmcnt(0)
	v_pk_fma_f32 v[124:125], v[124:125], v[128:129], v[132:133]
	v_pk_fma_f32 v[126:127], v[126:127], v[130:131], v[134:135]
	global_store_dwordx4 v[136:137], v[124:127], off
	global_load_dwordx4 v[124:127], v[144:145], off offset:64
	s_nop 0
	global_load_dwordx4 v[128:131], v[140:141], off offset:64
	v_mov_b32_e32 v135, v159
	v_mov_b32_e32 v134, v159
	v_mov_b32_e32 v133, v159
	v_mov_b32_e32 v132, v159
	s_waitcnt vmcnt(0)
	v_pk_fma_f32 v[120:121], v[120:121], v[124:125], v[128:129]
	v_pk_fma_f32 v[122:123], v[122:123], v[126:127], v[130:131]
	global_store_dwordx4 v[136:137], v[120:123], off offset:64
	global_load_dwordx4 v[120:123], v[144:145], off offset:128
	s_nop 0
	global_load_dwordx4 v[124:127], v[140:141], off offset:128
	v_mov_b32_e32 v131, v159
	s_waitcnt vmcnt(0)
	v_pk_fma_f32 v[116:117], v[116:117], v[120:121], v[124:125]
	v_pk_fma_f32 v[118:119], v[118:119], v[122:123], v[126:127]
	global_store_dwordx4 v[136:137], v[116:119], off offset:128
	global_load_dwordx4 v[116:119], v[144:145], off offset:192
	s_nop 0
	global_load_dwordx4 v[120:123], v[140:141], off offset:192
	v_or_b32_e32 v124, 48, v167
	v_cmp_lt_i32_e32 vcc, s40, v124
	v_add_u32_e32 v126, 0xffffc030, v167
	v_ashrrev_i32_e32 v125, 31, v124
	v_cndmask_b32_e64 v130, 0, 1, vcc
	v_cmp_gt_i32_e32 vcc, s73, v124
	v_or_b32_e32 v130, s2, v130
	v_mul_lo_u32 v192, v130, s33
	v_cndmask_b32_e32 v125, 0, v125, vcc
	v_cndmask_b32_e32 v124, v126, v124, vcc
	v_cndmask_b32_e32 v127, v162, v163, vcc
	v_cndmask_b32_e32 v126, v164, v165, vcc
	v_cndmask_b32_e32 v129, v166, v168, vcc
	v_cndmask_b32_e32 v128, v169, v170, vcc
	v_lshlrev_b64 v[124:125], 12, v[124:125]
	v_lshl_add_u64 v[126:127], v[126:127], 0, v[124:125]
	v_lshl_add_u64 v[124:125], v[128:129], 0, v[124:125]
	v_lshl_add_u64 v[128:129], s[0:1], 0, v[192:193]
	v_cndmask_b32_e64 v125, v127, v125, s[38:39]
	v_cndmask_b32_e64 v124, v126, v124, s[38:39]
	v_lshl_add_u64 v[128:129], v[128:129], 0, v[160:161]
	v_lshl_add_u64 v[124:125], v[124:125], 0, v[160:161]
	v_mov_b32_e32 v145, v159
	v_mov_b32_e32 v144, v159
	v_mov_b32_e32 v141, v159
	v_mov_b32_e32 v140, v159
	v_mov_b32_e32 v130, v159
	s_waitcnt vmcnt(0)
	v_pk_fma_f32 v[112:113], v[112:113], v[116:117], v[120:121]
	v_pk_fma_f32 v[114:115], v[114:115], v[118:119], v[122:123]
	global_store_dwordx4 v[136:137], v[112:115], off offset:192
	global_load_dwordx4 v[152:155], v[128:129], off
	global_load_dwordx4 v[148:151], v[124:125], off
	global_load_dwordx4 v[144:147], v[128:129], off offset:64
	global_load_dwordx4 v[140:143], v[124:125], off offset:64
	s_nop 0
	v_lshl_add_u64 v[120:121], v[126:127], 0, v[160:161]
	v_mov_b32_e32 v137, v159
	v_mov_b32_e32 v136, v159
	v_mov_b32_e32 v127, v159
	v_mov_b32_e32 v126, v159
	v_mov_b32_e32 v123, v159
	v_mov_b32_e32 v122, v159
	s_waitcnt vmcnt(2)
	v_pk_fma_f32 v[108:109], v[108:109], v[152:153], v[148:149]
	v_pk_fma_f32 v[110:111], v[110:111], v[154:155], v[150:151]
	global_store_dwordx4 v[120:121], v[108:111], off
	s_nop 0
	v_mov_b32_e32 v119, v159
	v_mov_b32_e32 v118, v159
	v_mov_b32_e32 v117, v159
	v_mov_b32_e32 v116, v159
	s_waitcnt vmcnt(1)
	v_pk_fma_f32 v[104:105], v[104:105], v[144:145], v[140:141]
	v_pk_fma_f32 v[106:107], v[106:107], v[146:147], v[142:143]
	global_store_dwordx4 v[120:121], v[104:107], off offset:64
	global_load_dwordx4 v[152:155], v[128:129], off offset:128
	global_load_dwordx4 v[148:151], v[124:125], off offset:128
	global_load_dwordx4 v[144:147], v[128:129], off offset:192
	global_load_dwordx4 v[140:143], v[124:125], off offset:192
	s_nop 0
	v_mov_b32_e32 v115, v159
	s_waitcnt vmcnt(2)
	v_pk_fma_f32 v[100:101], v[100:101], v[152:153], v[148:149]
	v_pk_fma_f32 v[102:103], v[102:103], v[154:155], v[150:151]
	global_store_dwordx4 v[120:121], v[100:103], off offset:128
	s_nop 0
	v_or_b32_e32 v108, 64, v167
	v_cmp_lt_i32_e32 vcc, s40, v108
	v_add_u32_e32 v110, 0xffffc040, v167
	v_ashrrev_i32_e32 v109, 31, v108
	v_cndmask_b32_e64 v114, 0, 1, vcc
	v_cmp_gt_i32_e32 vcc, s73, v108
	v_or_b32_e32 v114, s2, v114
	v_mul_lo_u32 v192, v114, s33
	v_cndmask_b32_e32 v109, 0, v109, vcc
	v_cndmask_b32_e32 v108, v110, v108, vcc
	v_cndmask_b32_e32 v111, v162, v163, vcc
	v_cndmask_b32_e32 v110, v164, v165, vcc
	v_cndmask_b32_e32 v113, v166, v168, vcc
	v_cndmask_b32_e32 v112, v169, v170, vcc
	v_lshlrev_b64 v[108:109], 12, v[108:109]
	v_lshl_add_u64 v[110:111], v[110:111], 0, v[108:109]
	v_lshl_add_u64 v[108:109], v[112:113], 0, v[108:109]
	v_lshl_add_u64 v[112:113], s[0:1], 0, v[192:193]
	v_cndmask_b32_e64 v109, v111, v109, s[38:39]
	v_cndmask_b32_e64 v108, v110, v108, s[38:39]
	v_lshl_add_u64 v[112:113], v[112:113], 0, v[160:161]
	v_lshl_add_u64 v[108:109], v[108:109], 0, v[160:161]
	v_mov_b32_e32 v129, v159
	v_mov_b32_e32 v128, v159
	v_mov_b32_e32 v125, v159
	v_mov_b32_e32 v124, v159
	v_mov_b32_e32 v114, v159
	s_waitcnt vmcnt(1)
; template <int MI, int BM, int BN, class ACC>
; DI void resid_epi(const Prm& p, ACC& acc, int row0, int col0, int l, int gchunk, int lane) {
;     ...
;   for (int i = 0; i < MI; ++i) {
;     const int row = row0 + i * 16 + (lane & 15);
;     float* xr = xrow(p, row);
;     const float* xs = (l == 0 && gchunk == 2) ? xrow_in(p, row) : (const float*)xr;
;     const float* gt = mod + (size_t)(l * 2 + (row >= S ? 1 : 0)) * 6144 + gchunk * D;
; #pragma unroll
;     for (int j = 0; j < 4; ++j) {
;       const int col = col0 + j * 16 + 4 * (lane >> 4);
;       const float4 g4 = *(const float4*)(gt + col); float4 xv = *(const float4*)(xs + col);
;       xv.x += g4.x * acc[i][j][0]; xv.y += g4.y * acc[i][j][1]; xv.z += g4.z * acc[i][j][2]; xv.w += g4.w * acc[i][j][3];
;       *(float4*)(xr + col) = xv;
;     }
	v_pk_fma_f32 v[96:97], v[96:97], v[144:145], v[140:141]
	v_pk_fma_f32 v[98:99], v[98:99], v[146:147], v[142:143]
	global_store_dwordx4 v[120:121], v[96:99], off offset:192
	global_load_dwordx4 v[152:155], v[112:113], off
	global_load_dwordx4 v[148:151], v[108:109], off
	global_load_dwordx4 v[144:147], v[112:113], off offset:64
	global_load_dwordx4 v[140:143], v[108:109], off offset:64
	global_load_dwordx4 v[136:139], v[112:113], off offset:128
	global_load_dwordx4 v[132:135], v[108:109], off offset:128
	global_load_dwordx4 v[128:131], v[112:113], off offset:192
	global_load_dwordx4 v[124:127], v[108:109], off offset:192
	s_nop 0
	v_lshl_add_u64 v[104:105], v[110:111], 0, v[160:161]
	v_mov_b32_e32 v121, v159
	v_mov_b32_e32 v120, v159
	v_mov_b32_e32 v111, v159
	v_mov_b32_e32 v110, v159
	v_mov_b32_e32 v107, v159
	v_mov_b32_e32 v106, v159
	s_waitcnt vmcnt(6)
	v_pk_fma_f32 v[92:93], v[92:93], v[152:153], v[148:149]
	v_pk_fma_f32 v[94:95], v[94:95], v[154:155], v[150:151]
	global_store_dwordx4 v[104:105], v[92:95], off
	s_nop 0
	v_mov_b32_e32 v103, v159
	v_mov_b32_e32 v102, v159
	v_mov_b32_e32 v101, v159
	v_mov_b32_e32 v100, v159
	s_waitcnt vmcnt(5)
	v_pk_fma_f32 v[88:89], v[88:89], v[144:145], v[140:141]
	v_pk_fma_f32 v[90:91], v[90:91], v[146:147], v[142:143]
	global_store_dwordx4 v[104:105], v[88:91], off offset:64
	s_nop 0
	v_mov_b32_e32 v99, v159
	s_waitcnt vmcnt(4)
	v_pk_fma_f32 v[84:85], v[84:85], v[136:137], v[132:133]
	v_pk_fma_f32 v[86:87], v[86:87], v[138:139], v[134:135]
	global_store_dwordx4 v[104:105], v[84:87], off offset:128
	s_nop 0
	v_or_b32_e32 v92, 0x50, v167
	v_cmp_lt_i32_e32 vcc, s40, v92
	v_add_u32_e32 v94, 0xffffc050, v167
	v_ashrrev_i32_e32 v93, 31, v92
	v_cndmask_b32_e64 v98, 0, 1, vcc
	v_cmp_gt_i32_e32 vcc, s73, v92
	v_or_b32_e32 v98, s2, v98
	v_mul_lo_u32 v192, v98, s33
	v_cndmask_b32_e32 v93, 0, v93, vcc
	v_cndmask_b32_e32 v92, v94, v92, vcc
	v_cndmask_b32_e32 v95, v162, v163, vcc
	v_cndmask_b32_e32 v94, v164, v165, vcc
	v_cndmask_b32_e32 v97, v166, v168, vcc
	v_cndmask_b32_e32 v96, v169, v170, vcc
	v_lshlrev_b64 v[92:93], 12, v[92:93]
	v_lshl_add_u64 v[94:95], v[94:95], 0, v[92:93]
	v_lshl_add_u64 v[92:93], v[96:97], 0, v[92:93]
	v_lshl_add_u64 v[96:97], s[0:1], 0, v[192:193]
	v_cndmask_b32_e64 v93, v95, v93, s[38:39]
	v_cndmask_b32_e64 v92, v94, v92, s[38:39]
	v_lshl_add_u64 v[96:97], v[96:97], 0, v[160:161]
	v_lshl_add_u64 v[92:93], v[92:93], 0, v[160:161]
	v_mov_b32_e32 v113, v159
	v_mov_b32_e32 v112, v159
	v_mov_b32_e32 v109, v159
	v_mov_b32_e32 v108, v159
	v_mov_b32_e32 v98, v159
	s_waitcnt vmcnt(3)
	v_pk_fma_f32 v[80:81], v[80:81], v[128:129], v[124:125]
	v_pk_fma_f32 v[82:83], v[82:83], v[130:131], v[126:127]
	global_store_dwordx4 v[104:105], v[80:83], off offset:192
	global_load_dwordx4 v[152:155], v[96:97], off
	global_load_dwordx4 v[148:151], v[92:93], off
	global_load_dwordx4 v[144:147], v[96:97], off offset:64
	global_load_dwordx4 v[140:143], v[92:93], off offset:64
	global_load_dwordx4 v[136:139], v[96:97], off offset:128
	global_load_dwordx4 v[132:135], v[92:93], off offset:128
	global_load_dwordx4 v[128:131], v[96:97], off offset:192
	global_load_dwordx4 v[124:127], v[92:93], off offset:192
	s_nop 0
	v_lshl_add_u64 v[88:89], v[94:95], 0, v[160:161]
	v_mov_b32_e32 v105, v159
	v_mov_b32_e32 v104, v159
	v_mov_b32_e32 v95, v159
	v_mov_b32_e32 v94, v159
	v_mov_b32_e32 v91, v159
	v_mov_b32_e32 v90, v159
	s_waitcnt vmcnt(6)
	v_pk_fma_f32 v[76:77], v[76:77], v[152:153], v[148:149]
	v_pk_fma_f32 v[78:79], v[78:79], v[154:155], v[150:151]
	global_store_dwordx4 v[88:89], v[76:79], off
	s_nop 0
	v_mov_b32_e32 v87, v159
	v_mov_b32_e32 v86, v159
	v_mov_b32_e32 v85, v159
	v_mov_b32_e32 v84, v159
	s_waitcnt vmcnt(5)
	v_pk_fma_f32 v[72:73], v[72:73], v[144:145], v[140:141]
	v_pk_fma_f32 v[74:75], v[74:75], v[146:147], v[142:143]
	global_store_dwordx4 v[88:89], v[72:75], off offset:64
	s_nop 0
	v_mov_b32_e32 v83, v159
	s_waitcnt vmcnt(4)
	v_pk_fma_f32 v[68:69], v[68:69], v[136:137], v[132:133]
	v_pk_fma_f32 v[70:71], v[70:71], v[138:139], v[134:135]
	global_store_dwordx4 v[88:89], v[68:71], off offset:128
	s_nop 0
	v_or_b32_e32 v76, 0x60, v167
	v_cmp_lt_i32_e32 vcc, s40, v76
	v_add_u32_e32 v78, 0xffffc060, v167
	v_ashrrev_i32_e32 v77, 31, v76
	v_cndmask_b32_e64 v82, 0, 1, vcc
	v_cmp_gt_i32_e32 vcc, s73, v76
	v_or_b32_e32 v82, s2, v82
	v_mul_lo_u32 v192, v82, s33
	v_cndmask_b32_e32 v77, 0, v77, vcc
	v_cndmask_b32_e32 v76, v78, v76, vcc
	v_cndmask_b32_e32 v79, v162, v163, vcc
	v_cndmask_b32_e32 v78, v164, v165, vcc
	v_cndmask_b32_e32 v81, v166, v168, vcc
	v_cndmask_b32_e32 v80, v169, v170, vcc
	v_lshlrev_b64 v[76:77], 12, v[76:77]
	v_lshl_add_u64 v[78:79], v[78:79], 0, v[76:77]
	v_lshl_add_u64 v[76:77], v[80:81], 0, v[76:77]
	v_lshl_add_u64 v[80:81], s[0:1], 0, v[192:193]
	v_cndmask_b32_e64 v77, v79, v77, s[38:39]
	v_cndmask_b32_e64 v76, v78, v76, s[38:39]
	v_lshl_add_u64 v[80:81], v[80:81], 0, v[160:161]
	v_lshl_add_u64 v[76:77], v[76:77], 0, v[160:161]
	v_mov_b32_e32 v97, v159
	v_mov_b32_e32 v96, v159
	v_mov_b32_e32 v93, v159
	v_mov_b32_e32 v92, v159
	v_mov_b32_e32 v82, v159
	s_waitcnt vmcnt(3)
; template <int MI, int BM, int BN, class ACC>
; DI void resid_epi(const Prm& p, ACC& acc, int row0, int col0, int l, int gchunk, int lane) {
;     ...
;   for (int i = 0; i < MI; ++i) {
;     const int row = row0 + i * 16 + (lane & 15);
;     float* xr = xrow(p, row);
;     const float* xs = (l == 0 && gchunk == 2) ? xrow_in(p, row) : (const float*)xr;
;     const float* gt = mod + (size_t)(l * 2 + (row >= S ? 1 : 0)) * 6144 + gchunk * D;
; #pragma unroll
;     for (int j = 0; j < 4; ++j) {
;       const int col = col0 + j * 16 + 4 * (lane >> 4);
;       const float4 g4 = *(const float4*)(gt + col); float4 xv = *(const float4*)(xs + col);
;       xv.x += g4.x * acc[i][j][0]; xv.y += g4.y * acc[i][j][1]; xv.z += g4.z * acc[i][j][2]; xv.w += g4.w * acc[i][j][3];
;       *(float4*)(xr + col) = xv;
;     }
	v_pk_fma_f32 v[64:65], v[64:65], v[128:129], v[124:125]
	v_pk_fma_f32 v[66:67], v[66:67], v[130:131], v[126:127]
	global_store_dwordx4 v[88:89], v[64:67], off offset:192
	global_load_dwordx4 v[152:155], v[80:81], off
	global_load_dwordx4 v[148:151], v[76:77], off
	global_load_dwordx4 v[144:147], v[80:81], off offset:64
	global_load_dwordx4 v[140:143], v[76:77], off offset:64
	global_load_dwordx4 v[136:139], v[80:81], off offset:128
	global_load_dwordx4 v[132:135], v[76:77], off offset:128
	global_load_dwordx4 v[128:131], v[80:81], off offset:192
	global_load_dwordx4 v[124:127], v[76:77], off offset:192
	s_nop 0
	v_lshl_add_u64 v[72:73], v[78:79], 0, v[160:161]
	v_mov_b32_e32 v89, v159
	v_mov_b32_e32 v88, v159
	v_mov_b32_e32 v79, v159
	v_mov_b32_e32 v78, v159
	v_mov_b32_e32 v75, v159
	v_mov_b32_e32 v74, v159
	s_waitcnt vmcnt(6)
	v_pk_fma_f32 v[60:61], v[60:61], v[152:153], v[148:149]
	v_pk_fma_f32 v[62:63], v[62:63], v[154:155], v[150:151]
	global_store_dwordx4 v[72:73], v[60:63], off
	s_nop 0
	v_mov_b32_e32 v71, v159
	v_mov_b32_e32 v70, v159
	v_mov_b32_e32 v69, v159
	v_mov_b32_e32 v68, v159
	s_waitcnt vmcnt(5)
	v_pk_fma_f32 v[56:57], v[56:57], v[144:145], v[140:141]
	v_pk_fma_f32 v[58:59], v[58:59], v[146:147], v[142:143]
	global_store_dwordx4 v[72:73], v[56:59], off offset:64
	s_nop 0
	v_mov_b32_e32 v67, v159
	s_waitcnt vmcnt(4)
	v_pk_fma_f32 v[52:53], v[52:53], v[136:137], v[132:133]
	v_pk_fma_f32 v[54:55], v[54:55], v[138:139], v[134:135]
	global_store_dwordx4 v[72:73], v[52:55], off offset:128
	s_nop 0
	v_or_b32_e32 v60, 0x70, v167
	v_cmp_lt_i32_e32 vcc, s40, v60
	v_add_u32_e32 v62, 0xffffc070, v167
	v_ashrrev_i32_e32 v61, 31, v60
	v_cndmask_b32_e64 v66, 0, 1, vcc
	v_cmp_gt_i32_e32 vcc, s73, v60
	v_or_b32_e32 v66, s2, v66
	v_mul_lo_u32 v192, v66, s33
	v_cndmask_b32_e32 v61, 0, v61, vcc
	v_cndmask_b32_e32 v60, v62, v60, vcc
	v_cndmask_b32_e32 v63, v162, v163, vcc
	v_cndmask_b32_e32 v62, v164, v165, vcc
	v_cndmask_b32_e32 v65, v166, v168, vcc
	v_cndmask_b32_e32 v64, v169, v170, vcc
	v_lshlrev_b64 v[60:61], 12, v[60:61]
	v_lshl_add_u64 v[62:63], v[62:63], 0, v[60:61]
	v_lshl_add_u64 v[60:61], v[64:65], 0, v[60:61]
	v_lshl_add_u64 v[64:65], s[0:1], 0, v[192:193]
	v_cndmask_b32_e64 v61, v63, v61, s[38:39]
	v_cndmask_b32_e64 v60, v62, v60, s[38:39]
	v_lshl_add_u64 v[64:65], v[64:65], 0, v[160:161]
	v_lshl_add_u64 v[60:61], v[60:61], 0, v[160:161]
	v_lshl_add_u64 v[168:169], v[62:63], 0, v[160:161]
	s_mov_b32 s40, 0
	v_mov_b32_e32 v81, v159
	v_mov_b32_e32 v80, v159
	v_mov_b32_e32 v77, v159
	v_mov_b32_e32 v76, v159
	v_mov_b32_e32 v66, v159
	v_mov_b32_e32 v63, v159
	v_mov_b32_e32 v62, v159
	s_waitcnt vmcnt(3)
	v_pk_fma_f32 v[48:49], v[48:49], v[128:129], v[124:125]
	v_pk_fma_f32 v[50:51], v[50:51], v[130:131], v[126:127]
	global_store_dwordx4 v[72:73], v[48:51], off offset:192
	global_load_dwordx4 v[152:155], v[64:65], off
	global_load_dwordx4 v[148:151], v[60:61], off
	global_load_dwordx4 v[144:147], v[64:65], off offset:64
	global_load_dwordx4 v[140:143], v[60:61], off offset:64
	global_load_dwordx4 v[136:139], v[64:65], off offset:128
	global_load_dwordx4 v[132:135], v[60:61], off offset:128
	global_load_dwordx4 v[128:131], v[64:65], off offset:192
	global_load_dwordx4 v[124:127], v[60:61], off offset:192
	s_nop 0
	v_mov_b32_e32 v73, v159
	v_mov_b32_e32 v72, v159
	v_mov_b32_e32 v59, v159
	v_mov_b32_e32 v58, v159
	v_mov_b32_e32 v57, v159
	v_mov_b32_e32 v56, v159
	s_waitcnt vmcnt(6)
	v_pk_fma_f32 v[44:45], v[44:45], v[152:153], v[148:149]
	v_pk_fma_f32 v[46:47], v[46:47], v[154:155], v[150:151]
	global_store_dwordx4 v[168:169], v[44:47], off
	s_nop 0
	v_mov_b32_e32 v55, v159
	v_mov_b32_e32 v54, v159
	v_mov_b32_e32 v53, v159
	v_mov_b32_e32 v52, v159
	s_waitcnt vmcnt(5)
	v_pk_fma_f32 v[40:41], v[40:41], v[144:145], v[140:141]
	v_pk_fma_f32 v[42:43], v[42:43], v[146:147], v[142:143]
	global_store_dwordx4 v[168:169], v[40:43], off offset:64
	s_nop 0
	v_mov_b32_e32 v51, v159
	v_mov_b32_e32 v50, v159
	v_mov_b32_e32 v49, v159
	v_mov_b32_e32 v48, v159
	s_waitcnt vmcnt(4)
	v_pk_fma_f32 v[36:37], v[36:37], v[136:137], v[132:133]
	v_pk_fma_f32 v[38:39], v[38:39], v[138:139], v[134:135]
	global_store_dwordx4 v[168:169], v[36:39], off offset:128
	v_mov_b32_e32 v65, v159
	v_mov_b32_e32 v64, v159
	v_mov_b32_e32 v61, v159
	v_mov_b32_e32 v60, v159
	v_mov_b32_e32 v47, v159
	v_mov_b32_e32 v46, v159
	v_mov_b32_e32 v45, v159
	v_mov_b32_e32 v44, v159
	v_mov_b32_e32 v43, v159
	v_mov_b32_e32 v42, v159
	v_mov_b32_e32 v41, v159
	v_mov_b32_e32 v40, v159
	v_mov_b32_e32 v39, v159
	v_mov_b32_e32 v38, v159
	v_mov_b32_e32 v37, v159
	v_mov_b32_e32 v36, v159
	s_waitcnt vmcnt(3)
	v_pk_fma_f32 v[128:129], v[0:1], v[128:129], v[124:125]
	v_pk_fma_f32 v[130:131], v[2:3], v[130:131], v[126:127]
	v_mov_b32_e32 v3, v159
	v_mov_b32_e32 v2, v159
	v_mov_b32_e32 v1, v159
	v_mov_b32_e32 v0, v159
	global_store_dwordx4 v[168:169], v[128:131], off offset:192
	s_nop 1
	v_mov_b32_e32 v124, v159
	v_mov_b32_e32 v125, v159
	v_mov_b32_e32 v126, v159
	v_mov_b32_e32 v127, v159
	v_mov_b32_e32 v128, v159
	v_mov_b32_e32 v129, v159
	v_mov_b32_e32 v130, v159
	v_mov_b32_e32 v131, v159
	v_mov_b32_e32 v132, v159
	v_mov_b32_e32 v133, v159
	v_mov_b32_e32 v134, v159
	v_mov_b32_e32 v135, v159
	v_mov_b32_e32 v136, v159
	v_mov_b32_e32 v137, v159
	v_mov_b32_e32 v138, v159
	v_mov_b32_e32 v139, v159
	v_mov_b32_e32 v140, v159
	v_mov_b32_e32 v141, v159
	v_mov_b32_e32 v142, v159
	v_mov_b32_e32 v143, v159
	v_mov_b32_e32 v144, v159
	v_mov_b32_e32 v145, v159
	v_mov_b32_e32 v146, v159
	v_mov_b32_e32 v147, v159
	v_mov_b32_e32 v148, v159
	v_mov_b32_e32 v149, v159
	v_mov_b32_e32 v150, v159
	v_mov_b32_e32 v151, v159
	v_mov_b32_e32 v152, v159
	v_mov_b32_e32 v153, v159
	v_mov_b32_e32 v154, v159
	v_mov_b32_e32 v155, v159

; template <int MI, int BM, int BN, class ACC>
; DI void resid_epi(const Prm& p, ACC& acc, int row0, int col0, int l, int gchunk, int lane) {
;     ...
;   for (int i = 0; i < MI; ++i) {
;     const int row = row0 + i * 16 + (lane & 15);
;     float* xr = xrow(p, row);
;     const float* xs = (l == 0 && gchunk == 2) ? xrow_in(p, row) : (const float*)xr;
;     const float* gt = mod + (size_t)(l * 2 + (row >= S ? 1 : 0)) * 6144 + gchunk * D;
; #pragma unroll
;     for (int j = 0; j < 4; ++j) {
;       const int col = col0 + j * 16 + 4 * (lane >> 4);
;       const float4 g4 = *(const float4*)(gt + col); float4 xv = *(const float4*)(xs + col);
;       xv.x += g4.x * acc[i][j][0]; xv.y += g4.y * acc[i][j][1]; xv.z += g4.z * acc[i][j][2]; xv.w += g4.w * acc[i][j][3];
;       *(float4*)(xr + col) = xv;
;     }
.LBB0_2629:
	v_lshl_add_u32 v162, s40, 8, v239
	v_cmp_gt_i32_e32 vcc, s73, v162
	v_add_u32_e32 v163, 0xffffc000, v162
	v_readlane_b32 s0, v253, 58
	v_ashrrev_i32_e32 v164, 31, v162
	v_cndmask_b32_e32 v168, v163, v162, vcc
	v_mov_b32_e32 v163, s0
	v_readlane_b32 s0, v253, 57
	v_cndmask_b32_e32 v169, 0, v164, vcc
	v_mov_b32_e32 v164, s65
	v_mov_b32_e32 v165, s0
	v_mov_b32_e32 v166, s64
	s_movk_i32 s39, 0x3fff
	v_cndmask_b32_e32 v171, v163, v164, vcc
	v_cndmask_b32_e32 v170, v165, v166, vcc
	v_cmp_lt_i32_e32 vcc, s39, v162
	v_lshl_add_u32 v160, s41, 8, v240
	v_readlane_b32 s0, v254, 23
	v_cndmask_b32_e64 v167, 0, 1, vcc
	v_or_b32_e32 v167, s2, v167
	v_ashrrev_i32_e32 v161, 31, v160
	v_lshlrev_b64 v[168:169], 12, v[168:169]
	v_mul_lo_u32 v192, v167, s33
	v_readlane_b32 s1, v254, 24
	v_lshl_add_u64 v[168:169], v[170:171], 0, v[168:169]
	v_lshlrev_b64 v[160:161], 2, v[160:161]
	v_lshl_add_u64 v[170:171], s[0:1], 0, v[192:193]
	v_lshl_add_u64 v[176:177], v[170:171], 0, v[160:161]
	v_lshl_add_u64 v[178:179], v[168:169], 0, v[160:161]
	global_load_dwordx4 v[168:171], v[176:177], off
	global_load_dwordx4 v[172:175], v[178:179], off
	s_add_i32 s31, s31, 1
	s_waitcnt vmcnt(0)
	v_pk_fma_f32 v[156:157], v[156:157], v[168:169], v[172:173]
	v_pk_fma_f32 v[158:159], v[158:159], v[170:171], v[174:175]
	global_store_dwordx4 v[178:179], v[156:159], off
	global_load_dwordx4 v[156:159], v[176:177], off offset:64
	s_nop 0
	global_load_dwordx4 v[168:171], v[178:179], off offset:64
	s_waitcnt vmcnt(0)
	v_pk_fma_f32 v[152:153], v[152:153], v[156:157], v[168:169]
	v_pk_fma_f32 v[154:155], v[154:155], v[158:159], v[170:171]
	global_store_dwordx4 v[178:179], v[152:155], off offset:64
	global_load_dwordx4 v[152:155], v[176:177], off offset:128
	s_nop 0
	global_load_dwordx4 v[156:159], v[178:179], off offset:128
	s_waitcnt vmcnt(0)
	v_pk_fma_f32 v[148:149], v[148:149], v[152:153], v[156:157]
	v_pk_fma_f32 v[150:151], v[150:151], v[154:155], v[158:159]
	global_store_dwordx4 v[178:179], v[148:151], off offset:128
	global_load_dwordx4 v[148:151], v[176:177], off offset:192
	s_nop 0
	global_load_dwordx4 v[152:155], v[178:179], off offset:192
	v_mov_b32_e32 v159, 0
	v_mov_b32_e32 v158, v159
	v_mov_b32_e32 v157, v159
	v_mov_b32_e32 v156, v159
	s_waitcnt vmcnt(0)
	v_pk_fma_f32 v[144:145], v[144:145], v[148:149], v[152:153]
	v_pk_fma_f32 v[146:147], v[146:147], v[150:151], v[154:155]
	v_or_b32_e32 v148, 16, v162
	global_store_dwordx4 v[178:179], v[144:147], off offset:192
	v_cmp_gt_i32_e32 vcc, s73, v148
	s_nop 0
	v_add_u32_e32 v144, 0xffffc010, v162
	v_ashrrev_i32_e32 v145, 31, v148
	v_cndmask_b32_e32 v145, 0, v145, vcc
	v_cndmask_b32_e32 v144, v144, v148, vcc
	v_cndmask_b32_e32 v147, v163, v164, vcc
	v_cndmask_b32_e32 v146, v165, v166, vcc
	v_lshlrev_b64 v[144:145], 12, v[144:145]
	v_cmp_lt_i32_e32 vcc, s39, v148
	v_lshl_add_u64 v[144:145], v[146:147], 0, v[144:145]
	v_lshl_add_u64 v[154:155], v[144:145], 0, v[160:161]
	v_cndmask_b32_e64 v146, 0, 1, vcc
	v_or_b32_e32 v146, s2, v146
	v_mul_lo_u32 v192, v146, s33
	v_lshl_add_u64 v[146:147], s[0:1], 0, v[192:193]
	v_lshl_add_u64 v[152:153], v[146:147], 0, v[160:161]
	global_load_dwordx4 v[144:147], v[152:153], off
	global_load_dwordx4 v[148:151], v[154:155], off
	s_waitcnt vmcnt(0)
	v_pk_fma_f32 v[140:141], v[140:141], v[144:145], v[148:149]
	v_pk_fma_f32 v[142:143], v[142:143], v[146:147], v[150:151]
	global_store_dwordx4 v[154:155], v[140:143], off
	global_load_dwordx4 v[140:143], v[152:153], off offset:64
	s_nop 0
	global_load_dwordx4 v[144:147], v[154:155], off offset:64
	v_mov_b32_e32 v151, v159
	v_mov_b32_e32 v150, v159
	v_mov_b32_e32 v149, v159
	v_mov_b32_e32 v148, v159
	s_waitcnt vmcnt(0)
	v_pk_fma_f32 v[136:137], v[136:137], v[140:141], v[144:145]
	v_pk_fma_f32 v[138:139], v[138:139], v[142:143], v[146:147]
	global_store_dwordx4 v[154:155], v[136:139], off offset:64
	global_load_dwordx4 v[136:139], v[152:153], off offset:128
	s_nop 0
	global_load_dwordx4 v[140:143], v[154:155], off offset:128
	v_mov_b32_e32 v147, v159
	v_mov_b32_e32 v146, v159
	v_mov_b32_e32 v145, v159
	v_mov_b32_e32 v144, v159
	s_waitcnt vmcnt(0)
	v_pk_fma_f32 v[132:133], v[132:133], v[136:137], v[140:141]
	v_pk_fma_f32 v[134:135], v[134:135], v[138:139], v[142:143]
	global_store_dwordx4 v[154:155], v[132:135], off offset:128
	global_load_dwordx4 v[132:135], v[152:153], off offset:192
	s_nop 0
	global_load_dwordx4 v[136:139], v[154:155], off offset:192
	v_mov_b32_e32 v153, v159
	v_mov_b32_e32 v152, v159
	v_mov_b32_e32 v143, v159
	v_mov_b32_e32 v142, v159
	v_mov_b32_e32 v141, v159
	v_mov_b32_e32 v140, v159
	s_waitcnt vmcnt(0)
	v_pk_fma_f32 v[128:129], v[128:129], v[132:133], v[136:137]
	v_pk_fma_f32 v[130:131], v[130:131], v[134:135], v[138:139]
	v_or_b32_e32 v132, 32, v162
	global_store_dwordx4 v[154:155], v[128:131], off offset:192
	v_cmp_gt_i32_e32 vcc, s73, v132
	v_mov_b32_e32 v155, v159
	v_add_u32_e32 v128, 0xffffc020, v162
	v_ashrrev_i32_e32 v129, 31, v132
	v_cndmask_b32_e32 v129, 0, v129, vcc
	v_cndmask_b32_e32 v128, v128, v132, vcc
	v_cndmask_b32_e32 v131, v163, v164, vcc
	v_cndmask_b32_e32 v130, v165, v166, vcc
	v_lshlrev_b64 v[128:129], 12, v[128:129]
	v_cmp_lt_i32_e32 vcc, s39, v132
	v_lshl_add_u64 v[128:129], v[130:131], 0, v[128:129]
	v_lshl_add_u64 v[138:139], v[128:129], 0, v[160:161]
	v_cndmask_b32_e64 v130, 0, 1, vcc
	v_or_b32_e32 v130, s2, v130
	v_mul_lo_u32 v192, v130, s33
	v_lshl_add_u64 v[130:131], s[0:1], 0, v[192:193]
	v_lshl_add_u64 v[136:137], v[130:131], 0, v[160:161]
	global_load_dwordx4 v[128:131], v[136:137], off
	global_load_dwordx4 v[132:135], v[138:139], off
	v_mov_b32_e32 v154, v159
	s_waitcnt vmcnt(0)
; template <int MI, int BM, int BN, class ACC>
; DI void resid_epi(const Prm& p, ACC& acc, int row0, int col0, int l, int gchunk, int lane) {
;     ...
;   for (int i = 0; i < MI; ++i) {
;     const int row = row0 + i * 16 + (lane & 15);
;     float* xr = xrow(p, row);
;     const float* xs = (l == 0 && gchunk == 2) ? xrow_in(p, row) : (const float*)xr;
;     const float* gt = mod + (size_t)(l * 2 + (row >= S ? 1 : 0)) * 6144 + gchunk * D;
; #pragma unroll
;     for (int j = 0; j < 4; ++j) {
;       const int col = col0 + j * 16 + 4 * (lane >> 4);
;       const float4 g4 = *(const float4*)(gt + col); float4 xv = *(const float4*)(xs + col);
;       xv.x += g4.x * acc[i][j][0]; xv.y += g4.y * acc[i][j][1]; xv.z += g4.z * acc[i][j][2]; xv.w += g4.w * acc[i][j][3];
;       *(float4*)(xr + col) = xv;
;     }
	v_pk_fma_f32 v[124:125], v[124:125], v[128:129], v[132:133]
	v_pk_fma_f32 v[126:127], v[126:127], v[130:131], v[134:135]
	global_store_dwordx4 v[138:139], v[124:127], off
	global_load_dwordx4 v[124:127], v[136:137], off offset:64
	s_nop 0
	global_load_dwordx4 v[128:131], v[138:139], off offset:64
	v_mov_b32_e32 v135, v159
	v_mov_b32_e32 v134, v159
	v_mov_b32_e32 v133, v159
	v_mov_b32_e32 v132, v159
	s_waitcnt vmcnt(0)
	v_pk_fma_f32 v[120:121], v[120:121], v[124:125], v[128:129]
	v_pk_fma_f32 v[122:123], v[122:123], v[126:127], v[130:131]
	global_store_dwordx4 v[138:139], v[120:123], off offset:64
	global_load_dwordx4 v[120:123], v[136:137], off offset:128
	s_nop 0
	global_load_dwordx4 v[124:127], v[138:139], off offset:128
	v_mov_b32_e32 v131, v159
	v_mov_b32_e32 v130, v159
	v_mov_b32_e32 v129, v159
	v_mov_b32_e32 v128, v159
	s_waitcnt vmcnt(0)
	v_pk_fma_f32 v[116:117], v[116:117], v[120:121], v[124:125]
	v_pk_fma_f32 v[118:119], v[118:119], v[122:123], v[126:127]
	global_store_dwordx4 v[138:139], v[116:119], off offset:128
	global_load_dwordx4 v[116:119], v[136:137], off offset:192
	s_nop 0
	global_load_dwordx4 v[120:123], v[138:139], off offset:192
	v_mov_b32_e32 v137, v159
	v_mov_b32_e32 v136, v159
	v_mov_b32_e32 v127, v159
	v_mov_b32_e32 v126, v159
	v_mov_b32_e32 v125, v159
	v_mov_b32_e32 v124, v159
	s_waitcnt vmcnt(0)
	v_pk_fma_f32 v[112:113], v[112:113], v[116:117], v[120:121]
	v_pk_fma_f32 v[114:115], v[114:115], v[118:119], v[122:123]
	v_or_b32_e32 v116, 48, v162
	global_store_dwordx4 v[138:139], v[112:115], off offset:192
	v_cmp_gt_i32_e32 vcc, s73, v116
	v_mov_b32_e32 v139, v159
	v_add_u32_e32 v112, 0xffffc030, v162
	v_ashrrev_i32_e32 v113, 31, v116
	v_cndmask_b32_e32 v113, 0, v113, vcc
	v_cndmask_b32_e32 v112, v112, v116, vcc
	v_cndmask_b32_e32 v115, v163, v164, vcc
	v_cndmask_b32_e32 v114, v165, v166, vcc
	v_lshlrev_b64 v[112:113], 12, v[112:113]
	v_cmp_lt_i32_e32 vcc, s39, v116
	v_lshl_add_u64 v[112:113], v[114:115], 0, v[112:113]
	v_lshl_add_u64 v[122:123], v[112:113], 0, v[160:161]
	v_cndmask_b32_e64 v114, 0, 1, vcc
	v_or_b32_e32 v114, s2, v114
	v_mul_lo_u32 v192, v114, s33
	v_lshl_add_u64 v[114:115], s[0:1], 0, v[192:193]
	v_lshl_add_u64 v[120:121], v[114:115], 0, v[160:161]
	global_load_dwordx4 v[152:155], v[120:121], off
	global_load_dwordx4 v[148:151], v[122:123], off
	global_load_dwordx4 v[144:147], v[120:121], off offset:64
	global_load_dwordx4 v[140:143], v[122:123], off offset:64
	v_mov_b32_e32 v138, v159
	s_waitcnt vmcnt(2)
	v_pk_fma_f32 v[108:109], v[108:109], v[152:153], v[148:149]
	v_pk_fma_f32 v[110:111], v[110:111], v[154:155], v[150:151]
	global_store_dwordx4 v[122:123], v[108:111], off
	s_nop 0
	v_mov_b32_e32 v119, v159
	v_mov_b32_e32 v118, v159
	v_mov_b32_e32 v117, v159
	v_mov_b32_e32 v116, v159
	s_waitcnt vmcnt(1)
	v_pk_fma_f32 v[104:105], v[104:105], v[144:145], v[140:141]
	v_pk_fma_f32 v[106:107], v[106:107], v[146:147], v[142:143]
	global_store_dwordx4 v[122:123], v[104:107], off offset:64
	global_load_dwordx4 v[152:155], v[120:121], off offset:128
	global_load_dwordx4 v[148:151], v[122:123], off offset:128
	global_load_dwordx4 v[144:147], v[120:121], off offset:192
	global_load_dwordx4 v[140:143], v[122:123], off offset:192
	s_nop 0
	v_mov_b32_e32 v115, v159
	v_mov_b32_e32 v114, v159
	v_mov_b32_e32 v113, v159
	v_mov_b32_e32 v112, v159
	s_waitcnt vmcnt(2)
	v_pk_fma_f32 v[100:101], v[100:101], v[152:153], v[148:149]
	v_pk_fma_f32 v[102:103], v[102:103], v[154:155], v[150:151]
	global_store_dwordx4 v[122:123], v[100:103], off offset:128
	s_nop 0
	v_mov_b32_e32 v121, v159
	v_mov_b32_e32 v120, v159
	v_mov_b32_e32 v111, v159
	v_mov_b32_e32 v110, v159
	v_mov_b32_e32 v109, v159
	v_mov_b32_e32 v108, v159
	s_waitcnt vmcnt(1)
	v_pk_fma_f32 v[96:97], v[96:97], v[144:145], v[140:141]
	v_pk_fma_f32 v[98:99], v[98:99], v[146:147], v[142:143]
	v_or_b32_e32 v100, 64, v162
	global_store_dwordx4 v[122:123], v[96:99], off offset:192
	v_cmp_gt_i32_e32 vcc, s73, v100
	v_mov_b32_e32 v123, v159
	v_add_u32_e32 v96, 0xffffc040, v162
	v_ashrrev_i32_e32 v97, 31, v100
	v_cndmask_b32_e32 v97, 0, v97, vcc
	v_cndmask_b32_e32 v96, v96, v100, vcc
	v_cndmask_b32_e32 v99, v163, v164, vcc
	v_cndmask_b32_e32 v98, v165, v166, vcc
	v_lshlrev_b64 v[96:97], 12, v[96:97]
	v_cmp_lt_i32_e32 vcc, s39, v100
	v_lshl_add_u64 v[96:97], v[98:99], 0, v[96:97]
	v_lshl_add_u64 v[106:107], v[96:97], 0, v[160:161]
	v_cndmask_b32_e64 v98, 0, 1, vcc
	v_or_b32_e32 v98, s2, v98
	v_mul_lo_u32 v192, v98, s33
	v_lshl_add_u64 v[98:99], s[0:1], 0, v[192:193]
	v_lshl_add_u64 v[104:105], v[98:99], 0, v[160:161]
	global_load_dwordx4 v[152:155], v[104:105], off
	global_load_dwordx4 v[148:151], v[106:107], off
	global_load_dwordx4 v[144:147], v[104:105], off offset:64
	global_load_dwordx4 v[140:143], v[106:107], off offset:64
	global_load_dwordx4 v[136:139], v[104:105], off offset:128
	global_load_dwordx4 v[132:135], v[106:107], off offset:128
	global_load_dwordx4 v[128:131], v[104:105], off offset:192
	global_load_dwordx4 v[124:127], v[106:107], off offset:192
	v_mov_b32_e32 v122, v159
	s_waitcnt vmcnt(6)
	v_pk_fma_f32 v[92:93], v[92:93], v[152:153], v[148:149]
	v_pk_fma_f32 v[94:95], v[94:95], v[154:155], v[150:151]
	global_store_dwordx4 v[106:107], v[92:95], off
	s_nop 0
	v_mov_b32_e32 v103, v159
	v_mov_b32_e32 v102, v159
	v_mov_b32_e32 v101, v159
	v_mov_b32_e32 v100, v159
	s_waitcnt vmcnt(5)
	v_pk_fma_f32 v[88:89], v[88:89], v[144:145], v[140:141]
	v_pk_fma_f32 v[90:91], v[90:91], v[146:147], v[142:143]
	global_store_dwordx4 v[106:107], v[88:91], off offset:64
	s_nop 0
	v_mov_b32_e32 v99, v159
	v_mov_b32_e32 v98, v159
	v_mov_b32_e32 v97, v159
	v_mov_b32_e32 v96, v159
	s_waitcnt vmcnt(4)
; template <int MI, int BM, int BN, class ACC>
; DI void resid_epi(const Prm& p, ACC& acc, int row0, int col0, int l, int gchunk, int lane) {
;     ...
;   for (int i = 0; i < MI; ++i) {
;     const int row = row0 + i * 16 + (lane & 15);
;     float* xr = xrow(p, row);
;     const float* xs = (l == 0 && gchunk == 2) ? xrow_in(p, row) : (const float*)xr;
;     const float* gt = mod + (size_t)(l * 2 + (row >= S ? 1 : 0)) * 6144 + gchunk * D;
; #pragma unroll
;     for (int j = 0; j < 4; ++j) {
;       const int col = col0 + j * 16 + 4 * (lane >> 4);
;       const float4 g4 = *(const float4*)(gt + col); float4 xv = *(const float4*)(xs + col);
;       xv.x += g4.x * acc[i][j][0]; xv.y += g4.y * acc[i][j][1]; xv.z += g4.z * acc[i][j][2]; xv.w += g4.w * acc[i][j][3];
;       *(float4*)(xr + col) = xv;
;     }
	v_pk_fma_f32 v[84:85], v[84:85], v[136:137], v[132:133]
	v_pk_fma_f32 v[86:87], v[86:87], v[138:139], v[134:135]
	global_store_dwordx4 v[106:107], v[84:87], off offset:128
	s_nop 0
	v_mov_b32_e32 v105, v159
	v_mov_b32_e32 v104, v159
	v_mov_b32_e32 v95, v159
	v_mov_b32_e32 v94, v159
	v_mov_b32_e32 v93, v159
	v_mov_b32_e32 v92, v159
	s_waitcnt vmcnt(3)
	v_pk_fma_f32 v[80:81], v[80:81], v[128:129], v[124:125]
	v_pk_fma_f32 v[82:83], v[82:83], v[130:131], v[126:127]
	v_or_b32_e32 v84, 0x50, v162
	global_store_dwordx4 v[106:107], v[80:83], off offset:192
	v_cmp_gt_i32_e32 vcc, s73, v84
	v_mov_b32_e32 v107, v159
	v_add_u32_e32 v80, 0xffffc050, v162
	v_ashrrev_i32_e32 v81, 31, v84
	v_cndmask_b32_e32 v81, 0, v81, vcc
	v_cndmask_b32_e32 v80, v80, v84, vcc
	v_cndmask_b32_e32 v83, v163, v164, vcc
	v_cndmask_b32_e32 v82, v165, v166, vcc
	v_lshlrev_b64 v[80:81], 12, v[80:81]
	v_cmp_lt_i32_e32 vcc, s39, v84
	v_lshl_add_u64 v[80:81], v[82:83], 0, v[80:81]
	v_lshl_add_u64 v[90:91], v[80:81], 0, v[160:161]
	v_cndmask_b32_e64 v82, 0, 1, vcc
	v_or_b32_e32 v82, s2, v82
	v_mul_lo_u32 v192, v82, s33
	v_lshl_add_u64 v[82:83], s[0:1], 0, v[192:193]
	v_lshl_add_u64 v[88:89], v[82:83], 0, v[160:161]
	global_load_dwordx4 v[152:155], v[88:89], off
	global_load_dwordx4 v[148:151], v[90:91], off
	global_load_dwordx4 v[144:147], v[88:89], off offset:64
	global_load_dwordx4 v[140:143], v[90:91], off offset:64
	global_load_dwordx4 v[136:139], v[88:89], off offset:128
	global_load_dwordx4 v[132:135], v[90:91], off offset:128
	global_load_dwordx4 v[128:131], v[88:89], off offset:192
	global_load_dwordx4 v[124:127], v[90:91], off offset:192
	v_mov_b32_e32 v106, v159
	s_waitcnt vmcnt(6)
	v_pk_fma_f32 v[76:77], v[76:77], v[152:153], v[148:149]
	v_pk_fma_f32 v[78:79], v[78:79], v[154:155], v[150:151]
	global_store_dwordx4 v[90:91], v[76:79], off
	s_nop 0
	v_mov_b32_e32 v87, v159
	v_mov_b32_e32 v86, v159
	v_mov_b32_e32 v85, v159
	v_mov_b32_e32 v84, v159
	s_waitcnt vmcnt(5)
	v_pk_fma_f32 v[72:73], v[72:73], v[144:145], v[140:141]
	v_pk_fma_f32 v[74:75], v[74:75], v[146:147], v[142:143]
	global_store_dwordx4 v[90:91], v[72:75], off offset:64
	s_nop 0
	v_mov_b32_e32 v83, v159
	v_mov_b32_e32 v82, v159
	v_mov_b32_e32 v81, v159
	v_mov_b32_e32 v80, v159
	s_waitcnt vmcnt(4)
	v_pk_fma_f32 v[68:69], v[68:69], v[136:137], v[132:133]
	v_pk_fma_f32 v[70:71], v[70:71], v[138:139], v[134:135]
	global_store_dwordx4 v[90:91], v[68:71], off offset:128
	s_nop 0
	v_mov_b32_e32 v89, v159
	v_mov_b32_e32 v88, v159
	v_mov_b32_e32 v79, v159
	v_mov_b32_e32 v78, v159
	v_mov_b32_e32 v77, v159
	v_mov_b32_e32 v76, v159
	s_waitcnt vmcnt(3)
	v_pk_fma_f32 v[64:65], v[64:65], v[128:129], v[124:125]
	v_pk_fma_f32 v[66:67], v[66:67], v[130:131], v[126:127]
	v_or_b32_e32 v68, 0x60, v162
	global_store_dwordx4 v[90:91], v[64:67], off offset:192
	v_cmp_gt_i32_e32 vcc, s73, v68
	v_mov_b32_e32 v91, v159
	v_add_u32_e32 v64, 0xffffc060, v162
	v_ashrrev_i32_e32 v65, 31, v68
	v_cndmask_b32_e32 v65, 0, v65, vcc
	v_cndmask_b32_e32 v64, v64, v68, vcc
	v_cndmask_b32_e32 v67, v163, v164, vcc
	v_cndmask_b32_e32 v66, v165, v166, vcc
	v_lshlrev_b64 v[64:65], 12, v[64:65]
	v_cmp_lt_i32_e32 vcc, s39, v68
	v_lshl_add_u64 v[64:65], v[66:67], 0, v[64:65]
	v_lshl_add_u64 v[74:75], v[64:65], 0, v[160:161]
	v_cndmask_b32_e64 v66, 0, 1, vcc
	v_or_b32_e32 v66, s2, v66
	v_mul_lo_u32 v192, v66, s33
	v_lshl_add_u64 v[66:67], s[0:1], 0, v[192:193]
	v_lshl_add_u64 v[72:73], v[66:67], 0, v[160:161]
	global_load_dwordx4 v[152:155], v[72:73], off
	global_load_dwordx4 v[148:151], v[74:75], off
	global_load_dwordx4 v[144:147], v[72:73], off offset:64
	global_load_dwordx4 v[140:143], v[74:75], off offset:64
	global_load_dwordx4 v[136:139], v[72:73], off offset:128
	global_load_dwordx4 v[132:135], v[74:75], off offset:128
	global_load_dwordx4 v[128:131], v[72:73], off offset:192
	global_load_dwordx4 v[124:127], v[74:75], off offset:192
	v_mov_b32_e32 v90, v159
	s_waitcnt vmcnt(6)
	v_pk_fma_f32 v[60:61], v[60:61], v[152:153], v[148:149]
	v_pk_fma_f32 v[62:63], v[62:63], v[154:155], v[150:151]
	global_store_dwordx4 v[74:75], v[60:63], off
	s_nop 0
	v_mov_b32_e32 v71, v159
	v_mov_b32_e32 v70, v159
	v_mov_b32_e32 v69, v159
	v_mov_b32_e32 v68, v159
	s_waitcnt vmcnt(5)
; template <int MI, int BM, int BN, class ACC>
; DI void resid_epi(const Prm& p, ACC& acc, int row0, int col0, int l, int gchunk, int lane) {
;     ...
;   for (int i = 0; i < MI; ++i) {
;     const int row = row0 + i * 16 + (lane & 15);
;     float* xr = xrow(p, row);
;     const float* xs = (l == 0 && gchunk == 2) ? xrow_in(p, row) : (const float*)xr;
;     const float* gt = mod + (size_t)(l * 2 + (row >= S ? 1 : 0)) * 6144 + gchunk * D;
; #pragma unroll
;     for (int j = 0; j < 4; ++j) {
;       const int col = col0 + j * 16 + 4 * (lane >> 4);
;       const float4 g4 = *(const float4*)(gt + col); float4 xv = *(const float4*)(xs + col);
;       xv.x += g4.x * acc[i][j][0]; xv.y += g4.y * acc[i][j][1]; xv.z += g4.z * acc[i][j][2]; xv.w += g4.w * acc[i][j][3];
;       *(float4*)(xr + col) = xv;
;     }
	v_pk_fma_f32 v[56:57], v[56:57], v[144:145], v[140:141]
	v_pk_fma_f32 v[58:59], v[58:59], v[146:147], v[142:143]
	global_store_dwordx4 v[74:75], v[56:59], off offset:64
	s_nop 0
	v_mov_b32_e32 v67, v159
	v_mov_b32_e32 v66, v159
	v_mov_b32_e32 v65, v159
	v_mov_b32_e32 v64, v159
	s_waitcnt vmcnt(4)
	v_pk_fma_f32 v[52:53], v[52:53], v[136:137], v[132:133]
	v_pk_fma_f32 v[54:55], v[54:55], v[138:139], v[134:135]
	global_store_dwordx4 v[74:75], v[52:55], off offset:128
	s_nop 0
	v_mov_b32_e32 v73, v159
	v_mov_b32_e32 v72, v159
	v_mov_b32_e32 v63, v159
	v_mov_b32_e32 v62, v159
	v_mov_b32_e32 v61, v159
	v_mov_b32_e32 v60, v159
	s_waitcnt vmcnt(3)
	v_pk_fma_f32 v[48:49], v[48:49], v[128:129], v[124:125]
	v_pk_fma_f32 v[50:51], v[50:51], v[130:131], v[126:127]
	v_or_b32_e32 v52, 0x70, v162
	global_store_dwordx4 v[74:75], v[48:51], off offset:192
	v_cmp_gt_i32_e32 vcc, s73, v52
	v_mov_b32_e32 v75, v159
	v_add_u32_e32 v48, 0xffffc070, v162
	v_ashrrev_i32_e32 v49, 31, v52
	v_cndmask_b32_e32 v49, 0, v49, vcc
	v_cndmask_b32_e32 v48, v48, v52, vcc
	v_cndmask_b32_e32 v51, v163, v164, vcc
	v_cndmask_b32_e32 v50, v165, v166, vcc
	v_lshlrev_b64 v[48:49], 12, v[48:49]
	v_cmp_lt_i32_e32 vcc, s39, v52
	v_lshl_add_u64 v[48:49], v[50:51], 0, v[48:49]
	v_lshl_add_u64 v[58:59], v[48:49], 0, v[160:161]
	v_cndmask_b32_e64 v50, 0, 1, vcc
	v_or_b32_e32 v50, s2, v50
	v_mul_lo_u32 v192, v50, s33
	v_lshl_add_u64 v[50:51], s[0:1], 0, v[192:193]
	v_lshl_add_u64 v[56:57], v[50:51], 0, v[160:161]
	global_load_dwordx4 v[152:155], v[56:57], off
	global_load_dwordx4 v[148:151], v[58:59], off
	global_load_dwordx4 v[144:147], v[56:57], off offset:64
	global_load_dwordx4 v[140:143], v[58:59], off offset:64
	global_load_dwordx4 v[136:139], v[56:57], off offset:128
	global_load_dwordx4 v[132:135], v[58:59], off offset:128
	global_load_dwordx4 v[128:131], v[56:57], off offset:192
	global_load_dwordx4 v[124:127], v[58:59], off offset:192
	s_mov_b32 s39, 0
	v_mov_b32_e32 v74, v159
	s_waitcnt vmcnt(6)
	v_pk_fma_f32 v[44:45], v[44:45], v[152:153], v[148:149]
	v_pk_fma_f32 v[46:47], v[46:47], v[154:155], v[150:151]
	global_store_dwordx4 v[58:59], v[44:47], off
	s_nop 0
	v_mov_b32_e32 v55, v159
	v_mov_b32_e32 v54, v159
	v_mov_b32_e32 v53, v159
	v_mov_b32_e32 v52, v159
	s_waitcnt vmcnt(5)
	v_pk_fma_f32 v[40:41], v[40:41], v[144:145], v[140:141]
	v_pk_fma_f32 v[42:43], v[42:43], v[146:147], v[142:143]
	global_store_dwordx4 v[58:59], v[40:43], off offset:64
	s_nop 0
	v_mov_b32_e32 v51, v159
	v_mov_b32_e32 v50, v159
	v_mov_b32_e32 v49, v159
	v_mov_b32_e32 v48, v159
	s_waitcnt vmcnt(4)
	v_pk_fma_f32 v[36:37], v[36:37], v[136:137], v[132:133]
	v_pk_fma_f32 v[38:39], v[38:39], v[138:139], v[134:135]
	global_store_dwordx4 v[58:59], v[36:39], off offset:128
	s_nop 0
	v_mov_b32_e32 v57, v159
	v_mov_b32_e32 v56, v159
	v_mov_b32_e32 v47, v159
	v_mov_b32_e32 v46, v159
	v_mov_b32_e32 v45, v159
	v_mov_b32_e32 v44, v159
	s_waitcnt vmcnt(3)
	v_pk_fma_f32 v[32:33], v[32:33], v[128:129], v[124:125]
	v_pk_fma_f32 v[34:35], v[34:35], v[130:131], v[126:127]
	global_store_dwordx4 v[58:59], v[32:35], off offset:192
	v_mov_b32_e32 v59, v159
	v_mov_b32_e32 v58, v159
	v_mov_b32_e32 v43, v159
	v_mov_b32_e32 v42, v159
	v_mov_b32_e32 v41, v159
	v_mov_b32_e32 v40, v159
	v_mov_b32_e32 v39, v159
	v_mov_b32_e32 v38, v159
	v_mov_b32_e32 v37, v159
	v_mov_b32_e32 v36, v159
	v_mov_b32_e32 v35, v159
	v_mov_b32_e32 v34, v159
	v_mov_b32_e32 v33, v159
	v_mov_b32_e32 v32, v159
	s_nop 1
	v_mov_b32_e32 v124, v159
	v_mov_b32_e32 v125, v159
	v_mov_b32_e32 v126, v159
	v_mov_b32_e32 v127, v159
	v_mov_b32_e32 v128, v159
	v_mov_b32_e32 v129, v159
	v_mov_b32_e32 v130, v159
	v_mov_b32_e32 v131, v159
	v_mov_b32_e32 v132, v159
	v_mov_b32_e32 v133, v159
	v_mov_b32_e32 v134, v159
	v_mov_b32_e32 v135, v159
	v_mov_b32_e32 v136, v159
	v_mov_b32_e32 v137, v159
	v_mov_b32_e32 v138, v159
	v_mov_b32_e32 v139, v159
	v_mov_b32_e32 v140, v159
	v_mov_b32_e32 v141, v159
	v_mov_b32_e32 v142, v159
	v_mov_b32_e32 v143, v159
	v_mov_b32_e32 v144, v159
	v_mov_b32_e32 v145, v159
	v_mov_b32_e32 v146, v159
	v_mov_b32_e32 v147, v159
	v_mov_b32_e32 v148, v159
	v_mov_b32_e32 v149, v159
	v_mov_b32_e32 v150, v159
	v_mov_b32_e32 v151, v159
	v_mov_b32_e32 v152, v159
	v_mov_b32_e32 v153, v159
	v_mov_b32_e32 v154, v159
	v_mov_b32_e32 v155, v159
